# attention: softmax quarters interleaved with PV MFMAs, trimmed MFMA->VALU nops; scan consumer hand-scheduled
# speedup vs baseline: 1.0138x; 1.0138x over previous
; __device__ __forceinline__ void attn_phase(const Args& a, LAS unsigned char* lds, const bf16* Qn, const bf16* Kn, const bf16* Vt, bf16* O, float* stash, int tid, int lane, int wave) {
;     ...
;                     const LAS unsigned char* kb = lds + (t & 1) * AT_BUF + n32 * 144 + hi * 16;
;                     f32x16 p0, p1;
; #pragma unroll
;                     for (int r = 0; r < 16; ++r) { p0[r] = 0.f; p1[r] = 0.f; }
;                     bf16x8 kf0[4], kf1[4];
; #pragma unroll
;                     for (int ds = 0; ds < 4; ++ds) { kf0[ds] = *(const LAS bf16x8*)(kb + ds * 32); kf1[ds] = *(const LAS bf16x8*)(kb + 32 * 144 + ds * 32); }
;                     const LAS unsigned char* vb = lds + (t & 1) * AT_BUF + AT_KB + n32 * 144 + hi * 16;
;                     bf16x8 vf[2][4];
; #pragma unroll
;                     for (int i = 0; i < 4; ++i) vf[0][i] = *(const LAS bf16x8*)(vb + i * 32 * 144);
;                     __builtin_amdgcn_sched_barrier(0);
;                     #pragma unroll
;                     for (int ds = 0; ds < 4; ++ds) {
;                         p0 = __builtin_amdgcn_mfma_f32_32x32x16_bf16(kf0[ds], qf[ds], p0, 0, 0, 0);
;                         p1 = __builtin_amdgcn_mfma_f32_32x32x16_bf16(kf1[ds], qf[ds], p1, 0, 0, 0);
;                     }
;                                         __builtin_amdgcn_sched_barrier(0);
;                     if (t == td) {
;                         asm volatile("" ::: "memory");
; #pragma unroll
;                         for (int r = 0; r < 16; ++r) { const int key = (r & 3) + 8 * (r >> 2) + 4 * hi; if (key > qloc) p0[r] = -INFINITY; if (key + 32 > qloc) p1[r] = -INFINITY; }
;                     }
;                     asm volatile("s_nop 15\n\ts_nop 7" : "+v"(p0), "+v"(p1));
;                     float mx, mxb;
;                     mx = max3f(p0[0], p0[1], p1[0]); mxb = max3f(p0[2], p0[3], p1[1]); mx = max3f(mx, p1[2], p1[3]);
; #pragma unroll
;                     for (int r = 4; r < 16; r += 4) { mx = max3f(mx, p0[r], p0[r + 1]); mxb = max3f(mxb, p0[r + 2], p0[r + 3]); mx = max3f(mx, p1[r], p1[r + 1]); mxb = max3f(mxb, p1[r + 2], p1[r + 3]); }
;                     mx = max3f(mx, mxb, mxb);
;                     { auto rr = __builtin_amdgcn_permlane32_swap(__float_as_uint(mx), __float_as_uint(mx), false, false); mx = max3f(__uint_as_float(rr[0]), __uint_as_float(rr[1]), mrun); }
.LBB0_110:
	v_add_u32_e32 v0, v161, v160
	ds_read_b128 v[80:83], v0
	ds_read_b128 v[198:201], v0 offset:32
	ds_read_b128 v[84:87], v0 offset:4608
	ds_read_b128 v[202:205], v0 offset:4640
	ds_read_b128 v[206:209], v0 offset:64
	ds_read_b128 v[210:213], v0 offset:96
	ds_read_b128 v[218:221], v0 offset:4672
	ds_read_b128 v[222:225], v0 offset:4704
	ds_read_b128 v[152:155], v0 offset:9216
	ds_read_b128 v[10:13], v0 offset:13824
	ds_read_b128 v[6:9], v0 offset:18432
	ds_read_b128 v[2:5], v0 offset:23040
	s_waitcnt lgkmcnt(11)
	v_mfma_f32_32x32x16_bf16 v[96:111], v[80:83], v[112:115], 0
	s_waitcnt lgkmcnt(9)
	v_mfma_f32_32x32x16_bf16 v[80:95], v[84:87], v[112:115], 0
	v_mfma_f32_32x32x16_bf16 v[96:111], v[198:201], v[116:119], v[96:111]
	s_waitcnt lgkmcnt(8)
	v_mfma_f32_32x32x16_bf16 v[80:95], v[202:205], v[116:119], v[80:95]
	s_waitcnt lgkmcnt(7)
	v_mfma_f32_32x32x16_bf16 v[96:111], v[206:209], v[120:123], v[96:111]
	s_waitcnt lgkmcnt(5)
	v_mfma_f32_32x32x16_bf16 v[80:95], v[218:221], v[120:123], v[80:95]
	v_mfma_f32_32x32x16_bf16 v[96:111], v[210:213], v[124:127], v[96:111]
	s_waitcnt lgkmcnt(4)
	v_mfma_f32_32x32x16_bf16 v[80:95], v[222:225], v[124:127], v[80:95]
	ds_read_b128 v[198:201], v0 offset:9248
	ds_read_b128 v[202:205], v0 offset:13856
	ds_read_b128 v[206:209], v0 offset:18464
	ds_read_b128 v[210:213], v0 offset:23072
	s_nop 7
	s_cmp_lg_u32 s30, s2
	s_cbranch_scc1 .Lat_nodiag_a
	v_cndmask_b32_e64 v14, v96, v248, s[42:43]
	v_cndmask_b32_e64 v80, v80, v248, s[44:45]
	v_cndmask_b32_e64 v97, v248, v97, s[46:47]
	v_cndmask_b32_e64 v96, v14, v96, s[46:47]
	v_cndmask_b32_e64 v81, v81, v248, s[48:49]
	v_cndmask_b32_e64 v98, v98, v248, s[50:51]
	v_cndmask_b32_e64 v82, v82, v248, s[52:53]
	v_cndmask_b32_e64 v99, v99, v248, s[54:55]
	v_cndmask_b32_e64 v83, v83, v248, s[56:57]
	v_cndmask_b32_e64 v100, v100, v248, s[58:59]
	v_cndmask_b32_e64 v84, v84, v248, s[60:61]
	v_cndmask_b32_e64 v101, v101, v248, s[62:63]
	v_cndmask_b32_e64 v85, v85, v248, s[64:65]
	v_cndmask_b32_e64 v102, v102, v248, s[66:67]
	v_cndmask_b32_e64 v86, v86, v248, s[68:69]
	v_cndmask_b32_e64 v103, v103, v248, s[70:71]
	v_cndmask_b32_e64 v87, v87, v248, s[72:73]
	v_cndmask_b32_e64 v104, v104, v248, s[74:75]
	v_cndmask_b32_e64 v88, v88, v248, s[76:77]
	v_cndmask_b32_e64 v105, v105, v248, s[78:79]
	v_cndmask_b32_e64 v89, v89, v248, s[80:81]
	v_cndmask_b32_e64 v106, v106, v248, s[82:83]
	v_cndmask_b32_e64 v90, v90, v248, s[84:85]
	v_cndmask_b32_e64 v107, v107, v248, s[86:87]
	v_cndmask_b32_e64 v91, v91, v248, s[88:89]
	v_cndmask_b32_e64 v108, v108, v248, s[90:91]
	v_cndmask_b32_e64 v92, v92, v248, s[92:93]
	v_cndmask_b32_e64 v109, v109, v248, s[94:95]
	v_cndmask_b32_e64 v93, v93, v248, s[96:97]
	v_cndmask_b32_e64 v110, v110, v248, s[6:7]
	v_cndmask_b32_e64 v94, v94, v248, s[8:9]
	v_cndmask_b32_e64 v111, v111, v248, s[10:11]
	v_cndmask_b32_e64 v95, v95, v248, s[12:13]
.Lat_nodiag_a:
	v_max3_f32 v14, v96, v97, v80
	v_max3_f32 v15, v98, v99, v81
	v_max3_f32 v14, v14, v82, v83
	v_max3_f32 v15, v15, v102, v103
	v_max3_f32 v14, v14, v100, v101
	v_max3_f32 v15, v15, v86, v87
	v_max3_f32 v14, v14, v84, v85
	v_max3_f32 v15, v15, v106, v107
	v_max3_f32 v14, v14, v104, v105
	v_max3_f32 v15, v15, v90, v91
	v_max3_f32 v14, v14, v88, v89
	v_max3_f32 v15, v15, v110, v111
	v_max3_f32 v14, v14, v108, v109
	v_max3_f32 v15, v15, v94, v95
	v_max3_f32 v14, v14, v92, v93
	v_max3_f32 v14, v14, v15, v15
	v_mov_b32_e32 v15, v14
	s_nop 1
	v_permlane32_swap_b32_e32 v14, v15
	v_max3_f32 v14, v14, v15, v194
	v_add_f32_e32 v15, 0x41000000, v194
	v_cmp_gt_f32_e32 vcc, v14, v15
	s_cbranch_vccz .Lat_noresc_a
	v_sub_f32_e32 v15, v194, v14
	v_exp_f32_e32 v194, v15
	s_nop 0
	v_pk_mul_f32 v[78:79], v[78:79], v[194:195] op_sel_hi:[1,0]
	v_pk_mul_f32 v[76:77], v[76:77], v[194:195] op_sel_hi:[1,0]
	v_pk_mul_f32 v[74:75], v[74:75], v[194:195] op_sel_hi:[1,0]
	v_pk_mul_f32 v[72:73], v[72:73], v[194:195] op_sel_hi:[1,0]
	v_pk_mul_f32 v[70:71], v[70:71], v[194:195] op_sel_hi:[1,0]
	v_pk_mul_f32 v[68:69], v[68:69], v[194:195] op_sel_hi:[1,0]
	v_pk_mul_f32 v[66:67], v[66:67], v[194:195] op_sel_hi:[1,0]
	v_pk_mul_f32 v[64:65], v[64:65], v[194:195] op_sel_hi:[1,0]
	v_pk_mul_f32 v[62:63], v[62:63], v[194:195] op_sel_hi:[1,0]
	v_pk_mul_f32 v[60:61], v[60:61], v[194:195] op_sel_hi:[1,0]
	v_pk_mul_f32 v[58:59], v[58:59], v[194:195] op_sel_hi:[1,0]
	v_pk_mul_f32 v[56:57], v[56:57], v[194:195] op_sel_hi:[1,0]
	v_pk_mul_f32 v[54:55], v[54:55], v[194:195] op_sel_hi:[1,0]
	v_pk_mul_f32 v[52:53], v[52:53], v[194:195] op_sel_hi:[1,0]
	v_pk_mul_f32 v[50:51], v[50:51], v[194:195] op_sel_hi:[1,0]
	v_pk_mul_f32 v[48:49], v[48:49], v[194:195] op_sel_hi:[1,0]
	v_pk_mul_f32 v[46:47], v[46:47], v[194:195] op_sel_hi:[1,0]
	v_pk_mul_f32 v[44:45], v[44:45], v[194:195] op_sel_hi:[1,0]
	v_pk_mul_f32 v[42:43], v[42:43], v[194:195] op_sel_hi:[1,0]
	v_pk_mul_f32 v[40:41], v[40:41], v[194:195] op_sel_hi:[1,0]
	v_pk_mul_f32 v[38:39], v[38:39], v[194:195] op_sel_hi:[1,0]
	v_pk_mul_f32 v[36:37], v[36:37], v[194:195] op_sel_hi:[1,0]
	v_pk_mul_f32 v[34:35], v[34:35], v[194:195] op_sel_hi:[1,0]
	v_pk_mul_f32 v[32:33], v[32:33], v[194:195] op_sel_hi:[1,0]
	v_pk_mul_f32 v[30:31], v[30:31], v[194:195] op_sel_hi:[1,0]
	v_pk_mul_f32 v[28:29], v[28:29], v[194:195] op_sel_hi:[1,0]
	v_pk_mul_f32 v[26:27], v[26:27], v[194:195] op_sel_hi:[1,0]
	v_pk_mul_f32 v[24:25], v[24:25], v[194:195] op_sel_hi:[1,0]
	v_pk_mul_f32 v[22:23], v[22:23], v[194:195] op_sel_hi:[1,0]
	v_pk_mul_f32 v[20:21], v[20:21], v[194:195] op_sel_hi:[1,0]
	v_pk_mul_f32 v[18:19], v[18:19], v[194:195] op_sel_hi:[1,0]
	v_pk_mul_f32 v[16:17], v[16:17], v[194:195] op_sel_hi:[1,0]
	v_mul_f32_e32 v197, v197, v194
	v_mov_b32_e32 v194, v14
; #define LAS __attribute__((address_space(3)))
; __device__ __forceinline__ void attn_phase(const Args& a, LAS unsigned char* lds, const bf16* Qn, const bf16* Kn, const bf16* Vt, bf16* O, float* stash, int tid, int lane, int wave) {
;     ...
;                     {
;                         const f32x2 mm2 = {mrun, mrun};
; #pragma unroll
;                         for (int r = 0; r < 16; r += 2) { const f32x2 a2 = (f32x2){p0[r], p0[r + 1]} - mm2, b2 = (f32x2){p1[r], p1[r + 1]} - mm2; p0[r] = a2.x; p0[r + 1] = a2.y; p1[r] = b2.x; p1[r + 1] = b2.y; }
;                     }
; #pragma unroll
;                     for (int r = 0; r < 16; ++r) { p0[r] = __builtin_amdgcn_exp2f(p0[r]); p1[r] = __builtin_amdgcn_exp2f(p1[r]); }
;                     {
;                         const f32x16 ps = p0 + p1;
;                         f32x2 s2 = (f32x2){ps[0], ps[1]} + (f32x2){ps[2], ps[3]};
; #pragma unroll
;                         for (int r = 4; r < 16; r += 2) s2 += (f32x2){ps[r], ps[r + 1]};
;                         lsum += s2.x + s2.y;
;                     }
;                     bf16x8 pf[4];
; #pragma unroll
;                     for (int s4 = 0; s4 < 4; ++s4) {
;                         u32x4 w;
;                         if (s4 < 2) { w.x = pk2(p0[8 * s4 + 0], p0[8 * s4 + 1]); w.y = pk2(p0[8 * s4 + 2], p0[8 * s4 + 3]); w.z = pk2(p0[8 * s4 + 4], p0[8 * s4 + 5]); w.w = pk2(p0[8 * s4 + 6], p0[8 * s4 + 7]); }
;                         else { const int q = s4 - 2; w.x = pk2(p1[8 * q + 0], p1[8 * q + 1]); w.y = pk2(p1[8 * q + 2], p1[8 * q + 3]); w.z = pk2(p1[8 * q + 4], p1[8 * q + 5]); w.w = pk2(p1[8 * q + 6], p1[8 * q + 7]); }
;                         pf[s4] = __builtin_bit_cast(bf16x8, w);
;                     }
; #pragma unroll
;                     for (int s4 = 0; s4 < 4; ++s4) {
;                         if (s4 + 1 < 4) {
; #pragma unroll
;                             for (int i = 0; i < 4; ++i) vf[(s4 + 1) & 1][i] = *(const LAS bf16x8*)(vb + i * 32 * 144 + (s4 + 1) * 32);
;                         }
;                         __builtin_amdgcn_sched_barrier(0);
;                         #pragma unroll
;                         for (int i = 0; i < 4; ++i) o[i] = __builtin_amdgcn_mfma_f32_32x32x16_bf16(vf[s4 & 1][i], pf[s4], o[i], 0, 0, 0);
;                                                 __builtin_amdgcn_sched_barrier(0);
;                     }
.Lat_noresc_a:
	v_sub_f32_e32 v96, v96, v194
	v_sub_f32_e32 v97, v97, v194
	v_sub_f32_e32 v98, v98, v194
	v_sub_f32_e32 v99, v99, v194
	v_sub_f32_e32 v100, v100, v194
	v_sub_f32_e32 v101, v101, v194
	v_sub_f32_e32 v102, v102, v194
	v_sub_f32_e32 v103, v103, v194
	v_exp_f32_e32 v96, v96
	v_exp_f32_e32 v97, v97
	v_exp_f32_e32 v98, v98
	v_exp_f32_e32 v99, v99
	v_exp_f32_e32 v100, v100
	v_exp_f32_e32 v101, v101
	v_exp_f32_e32 v102, v102
	v_exp_f32_e32 v103, v103
	v_add_f32_e32 v234, v96, v97
	v_add_f32_e32 v235, v98, v99
	v_add_f32_e32 v234, v234, v100
	v_add_f32_e32 v235, v235, v101
	v_add_f32_e32 v234, v234, v102
	v_add_f32_e32 v235, v235, v103
	v_cvt_pk_bf16_f32 v218, v96, v97
	v_cvt_pk_bf16_f32 v219, v98, v99
	v_cvt_pk_bf16_f32 v220, v100, v101
	v_cvt_pk_bf16_f32 v221, v102, v103
	v_add_f32_e32 v197, v197, v234
	v_add_f32_e32 v197, v197, v235
	s_waitcnt lgkmcnt(7)
	v_mfma_f32_32x32x16_bf16 v[64:79], v[152:155], v[218:221], v[64:79]
	v_sub_f32_e32 v104, v104, v194
	v_sub_f32_e32 v105, v105, v194
	v_sub_f32_e32 v106, v106, v194
	v_sub_f32_e32 v107, v107, v194
	v_sub_f32_e32 v108, v108, v194
	v_sub_f32_e32 v109, v109, v194
	v_sub_f32_e32 v110, v110, v194
	s_waitcnt lgkmcnt(6)
	v_mfma_f32_32x32x16_bf16 v[48:63], v[10:13], v[218:221], v[48:63]
	v_sub_f32_e32 v111, v111, v194
	v_exp_f32_e32 v104, v104
	v_exp_f32_e32 v105, v105
	v_exp_f32_e32 v106, v106
	v_exp_f32_e32 v107, v107
	v_exp_f32_e32 v108, v108
	v_exp_f32_e32 v109, v109
	s_waitcnt lgkmcnt(5)
	v_mfma_f32_32x32x16_bf16 v[32:47], v[6:9], v[218:221], v[32:47]
	v_exp_f32_e32 v110, v110
	v_exp_f32_e32 v111, v111
	v_add_f32_e32 v234, v104, v105
	v_add_f32_e32 v235, v106, v107
	v_add_f32_e32 v234, v234, v108
	v_add_f32_e32 v235, v235, v109
	v_add_f32_e32 v234, v234, v110
	s_waitcnt lgkmcnt(4)
	v_mfma_f32_32x32x16_bf16 v[16:31], v[2:5], v[218:221], v[16:31]
	v_add_f32_e32 v235, v235, v111
	v_cvt_pk_bf16_f32 v222, v104, v105
	v_cvt_pk_bf16_f32 v223, v106, v107
	v_cvt_pk_bf16_f32 v224, v108, v109
	v_cvt_pk_bf16_f32 v225, v110, v111
	v_add_f32_e32 v197, v197, v234
	v_add_f32_e32 v197, v197, v235
	ds_read_b128 v[152:155], v0 offset:9280
	ds_read_b128 v[10:13], v0 offset:13888
	ds_read_b128 v[6:9], v0 offset:18496
	ds_read_b128 v[2:5], v0 offset:23104
	s_waitcnt lgkmcnt(7)
	v_mfma_f32_32x32x16_bf16 v[64:79], v[198:201], v[222:225], v[64:79]
	v_sub_f32_e32 v80, v80, v194
	v_sub_f32_e32 v81, v81, v194
	v_sub_f32_e32 v82, v82, v194
	v_sub_f32_e32 v83, v83, v194
	v_sub_f32_e32 v84, v84, v194
	v_sub_f32_e32 v85, v85, v194
	v_sub_f32_e32 v86, v86, v194
	s_waitcnt lgkmcnt(6)
	v_mfma_f32_32x32x16_bf16 v[48:63], v[202:205], v[222:225], v[48:63]
	v_sub_f32_e32 v87, v87, v194
	v_exp_f32_e32 v80, v80
	v_exp_f32_e32 v81, v81
	v_exp_f32_e32 v82, v82
	v_exp_f32_e32 v83, v83
	v_exp_f32_e32 v84, v84
	v_exp_f32_e32 v85, v85
	s_waitcnt lgkmcnt(5)
	v_mfma_f32_32x32x16_bf16 v[32:47], v[206:209], v[222:225], v[32:47]
	v_exp_f32_e32 v86, v86
	v_exp_f32_e32 v87, v87
	v_add_f32_e32 v234, v80, v81
	v_add_f32_e32 v235, v82, v83
	v_add_f32_e32 v234, v234, v84
	v_add_f32_e32 v235, v235, v85
	v_add_f32_e32 v234, v234, v86
	s_waitcnt lgkmcnt(4)
	v_mfma_f32_32x32x16_bf16 v[16:31], v[210:213], v[222:225], v[16:31]
	v_add_f32_e32 v235, v235, v87
	v_cvt_pk_bf16_f32 v226, v80, v81
	v_cvt_pk_bf16_f32 v227, v82, v83
	v_cvt_pk_bf16_f32 v228, v84, v85
	v_cvt_pk_bf16_f32 v229, v86, v87
	v_add_f32_e32 v197, v197, v234
	v_add_f32_e32 v197, v197, v235
	ds_read_b128 v[198:201], v0 offset:9312
	ds_read_b128 v[202:205], v0 offset:13920
	ds_read_b128 v[206:209], v0 offset:18528
	ds_read_b128 v[210:213], v0 offset:23136
	s_waitcnt lgkmcnt(7)
	v_mfma_f32_32x32x16_bf16 v[64:79], v[152:155], v[226:229], v[64:79]
	v_sub_f32_e32 v88, v88, v194
	v_sub_f32_e32 v89, v89, v194
	v_sub_f32_e32 v90, v90, v194
	v_sub_f32_e32 v91, v91, v194
	v_sub_f32_e32 v92, v92, v194
	v_sub_f32_e32 v93, v93, v194
	v_sub_f32_e32 v94, v94, v194
	s_waitcnt lgkmcnt(6)
	v_mfma_f32_32x32x16_bf16 v[48:63], v[10:13], v[226:229], v[48:63]
	v_sub_f32_e32 v95, v95, v194
	v_exp_f32_e32 v88, v88
	v_exp_f32_e32 v89, v89
	v_exp_f32_e32 v90, v90
	v_exp_f32_e32 v91, v91
	v_exp_f32_e32 v92, v92
	v_exp_f32_e32 v93, v93
	s_waitcnt lgkmcnt(5)
	v_mfma_f32_32x32x16_bf16 v[32:47], v[6:9], v[226:229], v[32:47]
	v_exp_f32_e32 v94, v94
	v_exp_f32_e32 v95, v95
	v_add_f32_e32 v234, v88, v89
	v_add_f32_e32 v235, v90, v91
	v_add_f32_e32 v234, v234, v92
	v_add_f32_e32 v235, v235, v93
	v_add_f32_e32 v234, v234, v94
	s_waitcnt lgkmcnt(4)
	v_mfma_f32_32x32x16_bf16 v[16:31], v[2:5], v[226:229], v[16:31]
	v_add_f32_e32 v235, v235, v95
	v_cvt_pk_bf16_f32 v230, v88, v89
	v_cvt_pk_bf16_f32 v231, v90, v91
	v_cvt_pk_bf16_f32 v232, v92, v93
	v_cvt_pk_bf16_f32 v233, v94, v95
	v_add_f32_e32 v197, v197, v234
	v_add_f32_e32 v197, v197, v235
	s_waitcnt lgkmcnt(3)
	v_mfma_f32_32x32x16_bf16 v[64:79], v[198:201], v[230:233], v[64:79]
	s_waitcnt lgkmcnt(2)
	v_mfma_f32_32x32x16_bf16 v[48:63], v[202:205], v[230:233], v[48:63]
	s_waitcnt lgkmcnt(1)
	v_mfma_f32_32x32x16_bf16 v[32:47], v[206:209], v[230:233], v[32:47]
	s_waitcnt lgkmcnt(0)
	v_mfma_f32_32x32x16_bf16 v[16:31], v[210:213], v[230:233], v[16:31]
	s_add_i32 s22, s2, 1
	s_cmp_ge_u32 s22, s33
	s_cbranch_scc1 .LBB0_120

; #define LAS __attribute__((address_space(3)))
; __device__ __forceinline__ void attn_phase(const Args& a, LAS unsigned char* lds, const bf16* Qn, const bf16* Kn, const bf16* Vt, bf16* O, float* stash, int tid, int lane, int wave) {
;     ...
;                     const LAS unsigned char* kb = lds + (t & 1) * AT_BUF + n32 * 144 + hi * 16;
;                     f32x16 p0, p1;
; #pragma unroll
;                     for (int r = 0; r < 16; ++r) { p0[r] = 0.f; p1[r] = 0.f; }
;                     bf16x8 kf0[4], kf1[4];
; #pragma unroll
;                     for (int ds = 0; ds < 4; ++ds) { kf0[ds] = *(const LAS bf16x8*)(kb + ds * 32); kf1[ds] = *(const LAS bf16x8*)(kb + 32 * 144 + ds * 32); }
;                     const LAS unsigned char* vb = lds + (t & 1) * AT_BUF + AT_KB + n32 * 144 + hi * 16;
;                     bf16x8 vf[2][4];
; #pragma unroll
;                     for (int i = 0; i < 4; ++i) vf[0][i] = *(const LAS bf16x8*)(vb + i * 32 * 144);
;                     __builtin_amdgcn_sched_barrier(0);
;                     #pragma unroll
;                     for (int ds = 0; ds < 4; ++ds) {
;                         p0 = __builtin_amdgcn_mfma_f32_32x32x16_bf16(kf0[ds], qf[ds], p0, 0, 0, 0);
;                         p1 = __builtin_amdgcn_mfma_f32_32x32x16_bf16(kf1[ds], qf[ds], p1, 0, 0, 0);
;                     }
;                                         __builtin_amdgcn_sched_barrier(0);
;                     if (t == td) {
;                         asm volatile("" ::: "memory");
; #pragma unroll
;                         for (int r = 0; r < 16; ++r) { const int key = (r & 3) + 8 * (r >> 2) + 4 * hi; if (key > qloc) p0[r] = -INFINITY; if (key + 32 > qloc) p1[r] = -INFINITY; }
.LBB0_127:
	v_add_u32_e32 v0, v161, v160
	ds_read_b128 v[80:83], v0 offset:27648
	ds_read_b128 v[198:201], v0 offset:27680
	ds_read_b128 v[84:87], v0 offset:32256
	ds_read_b128 v[202:205], v0 offset:32288
	ds_read_b128 v[206:209], v0 offset:27712
	ds_read_b128 v[210:213], v0 offset:27744
	ds_read_b128 v[218:221], v0 offset:32320
	ds_read_b128 v[222:225], v0 offset:32352
	ds_read_b128 v[152:155], v0 offset:36864
	ds_read_b128 v[10:13], v0 offset:41472
	ds_read_b128 v[6:9], v0 offset:46080
	ds_read_b128 v[2:5], v0 offset:50688
	s_waitcnt lgkmcnt(11)
	v_mfma_f32_32x32x16_bf16 v[96:111], v[80:83], v[112:115], 0
	s_waitcnt lgkmcnt(9)
	v_mfma_f32_32x32x16_bf16 v[80:95], v[84:87], v[112:115], 0
	v_mfma_f32_32x32x16_bf16 v[96:111], v[198:201], v[116:119], v[96:111]
	s_waitcnt lgkmcnt(8)
	v_mfma_f32_32x32x16_bf16 v[80:95], v[202:205], v[116:119], v[80:95]
	s_waitcnt lgkmcnt(7)
	v_mfma_f32_32x32x16_bf16 v[96:111], v[206:209], v[120:123], v[96:111]
	s_waitcnt lgkmcnt(5)
	v_mfma_f32_32x32x16_bf16 v[80:95], v[218:221], v[120:123], v[80:95]
	v_mfma_f32_32x32x16_bf16 v[96:111], v[210:213], v[124:127], v[96:111]
	s_waitcnt lgkmcnt(4)
	v_mfma_f32_32x32x16_bf16 v[80:95], v[222:225], v[124:127], v[80:95]
	ds_read_b128 v[198:201], v0 offset:36896
	ds_read_b128 v[202:205], v0 offset:41504
	ds_read_b128 v[206:209], v0 offset:46112
	ds_read_b128 v[210:213], v0 offset:50720
	s_nop 7
	s_cmp_lg_u32 s31, s2
	s_cbranch_scc1 .Lat_nodiag_b
	v_cndmask_b32_e64 v14, v96, v248, s[42:43]
	v_cndmask_b32_e64 v80, v80, v248, s[44:45]
	v_cndmask_b32_e64 v97, v248, v97, s[46:47]
	v_cndmask_b32_e64 v96, v14, v96, s[46:47]
	v_cndmask_b32_e64 v81, v81, v248, s[48:49]
	v_cndmask_b32_e64 v98, v98, v248, s[50:51]
	v_cndmask_b32_e64 v82, v82, v248, s[52:53]
	v_cndmask_b32_e64 v99, v99, v248, s[54:55]
	v_cndmask_b32_e64 v83, v83, v248, s[56:57]
	v_cndmask_b32_e64 v100, v100, v248, s[58:59]
	v_cndmask_b32_e64 v84, v84, v248, s[60:61]
	v_cndmask_b32_e64 v101, v101, v248, s[62:63]
	v_cndmask_b32_e64 v85, v85, v248, s[64:65]
	v_cndmask_b32_e64 v102, v102, v248, s[66:67]
	v_cndmask_b32_e64 v86, v86, v248, s[68:69]
	v_cndmask_b32_e64 v103, v103, v248, s[70:71]
	v_cndmask_b32_e64 v87, v87, v248, s[72:73]
	v_cndmask_b32_e64 v104, v104, v248, s[74:75]
	v_cndmask_b32_e64 v88, v88, v248, s[76:77]
	v_cndmask_b32_e64 v105, v105, v248, s[78:79]
	v_cndmask_b32_e64 v89, v89, v248, s[80:81]
	v_cndmask_b32_e64 v106, v106, v248, s[82:83]
	v_cndmask_b32_e64 v90, v90, v248, s[84:85]
	v_cndmask_b32_e64 v107, v107, v248, s[86:87]
	v_cndmask_b32_e64 v91, v91, v248, s[88:89]
	v_cndmask_b32_e64 v108, v108, v248, s[90:91]
	v_cndmask_b32_e64 v92, v92, v248, s[92:93]
	v_cndmask_b32_e64 v109, v109, v248, s[94:95]
	v_cndmask_b32_e64 v93, v93, v248, s[96:97]
	v_cndmask_b32_e64 v110, v110, v248, s[6:7]
	v_cndmask_b32_e64 v94, v94, v248, s[8:9]
	v_cndmask_b32_e64 v111, v111, v248, s[10:11]
	v_cndmask_b32_e64 v95, v95, v248, s[12:13]

; #define LAS __attribute__((address_space(3)))
; __device__ __forceinline__ void attn_phase(const Args& a, LAS unsigned char* lds, const bf16* Qn, const bf16* Kn, const bf16* Vt, bf16* O, float* stash, int tid, int lane, int wave) {
;     ...
;                     {
;                         const f32x2 mm2 = {mrun, mrun};
; #pragma unroll
;                         for (int r = 0; r < 16; r += 2) { const f32x2 a2 = (f32x2){p0[r], p0[r + 1]} - mm2, b2 = (f32x2){p1[r], p1[r + 1]} - mm2; p0[r] = a2.x; p0[r + 1] = a2.y; p1[r] = b2.x; p1[r + 1] = b2.y; }
;                     }
; #pragma unroll
;                     for (int r = 0; r < 16; ++r) { p0[r] = __builtin_amdgcn_exp2f(p0[r]); p1[r] = __builtin_amdgcn_exp2f(p1[r]); }
;                     {
;                         const f32x16 ps = p0 + p1;
;                         f32x2 s2 = (f32x2){ps[0], ps[1]} + (f32x2){ps[2], ps[3]};
; #pragma unroll
;                         for (int r = 4; r < 16; r += 2) s2 += (f32x2){ps[r], ps[r + 1]};
;                         lsum += s2.x + s2.y;
;                     }
;                     bf16x8 pf[4];
; #pragma unroll
;                     for (int s4 = 0; s4 < 4; ++s4) {
;                         u32x4 w;
;                         if (s4 < 2) { w.x = pk2(p0[8 * s4 + 0], p0[8 * s4 + 1]); w.y = pk2(p0[8 * s4 + 2], p0[8 * s4 + 3]); w.z = pk2(p0[8 * s4 + 4], p0[8 * s4 + 5]); w.w = pk2(p0[8 * s4 + 6], p0[8 * s4 + 7]); }
;                         else { const int q = s4 - 2; w.x = pk2(p1[8 * q + 0], p1[8 * q + 1]); w.y = pk2(p1[8 * q + 2], p1[8 * q + 3]); w.z = pk2(p1[8 * q + 4], p1[8 * q + 5]); w.w = pk2(p1[8 * q + 6], p1[8 * q + 7]); }
;                         pf[s4] = __builtin_bit_cast(bf16x8, w);
;                     }
; #pragma unroll
;                     for (int s4 = 0; s4 < 4; ++s4) {
;                         if (s4 + 1 < 4) {
; #pragma unroll
;                             for (int i = 0; i < 4; ++i) vf[(s4 + 1) & 1][i] = *(const LAS bf16x8*)(vb + i * 32 * 144 + (s4 + 1) * 32);
;                         }
;                         __builtin_amdgcn_sched_barrier(0);
;                         #pragma unroll
;                         for (int i = 0; i < 4; ++i) o[i] = __builtin_amdgcn_mfma_f32_32x32x16_bf16(vf[s4 & 1][i], pf[s4], o[i], 0, 0, 0);
;                                                 __builtin_amdgcn_sched_barrier(0);
;                     }
.Lat_noresc_b:
	v_sub_f32_e32 v96, v96, v194
	v_sub_f32_e32 v97, v97, v194
	v_sub_f32_e32 v98, v98, v194
	v_sub_f32_e32 v99, v99, v194
	v_sub_f32_e32 v100, v100, v194
	v_sub_f32_e32 v101, v101, v194
	v_sub_f32_e32 v102, v102, v194
	v_sub_f32_e32 v103, v103, v194
	v_exp_f32_e32 v96, v96
	v_exp_f32_e32 v97, v97
	v_exp_f32_e32 v98, v98
	v_exp_f32_e32 v99, v99
	v_exp_f32_e32 v100, v100
	v_exp_f32_e32 v101, v101
	v_exp_f32_e32 v102, v102
	v_exp_f32_e32 v103, v103
	v_add_f32_e32 v234, v96, v97
	v_add_f32_e32 v235, v98, v99
	v_add_f32_e32 v234, v234, v100
	v_add_f32_e32 v235, v235, v101
	v_add_f32_e32 v234, v234, v102
	v_add_f32_e32 v235, v235, v103
	v_cvt_pk_bf16_f32 v218, v96, v97
	v_cvt_pk_bf16_f32 v219, v98, v99
	v_cvt_pk_bf16_f32 v220, v100, v101
	v_cvt_pk_bf16_f32 v221, v102, v103
	v_add_f32_e32 v197, v197, v234
	v_add_f32_e32 v197, v197, v235
	s_waitcnt lgkmcnt(7)
	v_mfma_f32_32x32x16_bf16 v[64:79], v[152:155], v[218:221], v[64:79]
	v_sub_f32_e32 v104, v104, v194
	v_sub_f32_e32 v105, v105, v194
	v_sub_f32_e32 v106, v106, v194
	v_sub_f32_e32 v107, v107, v194
	v_sub_f32_e32 v108, v108, v194
	v_sub_f32_e32 v109, v109, v194
	v_sub_f32_e32 v110, v110, v194
	s_waitcnt lgkmcnt(6)
	v_mfma_f32_32x32x16_bf16 v[48:63], v[10:13], v[218:221], v[48:63]
	v_sub_f32_e32 v111, v111, v194
	v_exp_f32_e32 v104, v104
	v_exp_f32_e32 v105, v105
	v_exp_f32_e32 v106, v106
	v_exp_f32_e32 v107, v107
	v_exp_f32_e32 v108, v108
	v_exp_f32_e32 v109, v109
	s_waitcnt lgkmcnt(5)
	v_mfma_f32_32x32x16_bf16 v[32:47], v[6:9], v[218:221], v[32:47]
	v_exp_f32_e32 v110, v110
	v_exp_f32_e32 v111, v111
	v_add_f32_e32 v234, v104, v105
	v_add_f32_e32 v235, v106, v107
	v_add_f32_e32 v234, v234, v108
	v_add_f32_e32 v235, v235, v109
	v_add_f32_e32 v234, v234, v110
	s_waitcnt lgkmcnt(4)
	v_mfma_f32_32x32x16_bf16 v[16:31], v[2:5], v[218:221], v[16:31]
	v_add_f32_e32 v235, v235, v111
	v_cvt_pk_bf16_f32 v222, v104, v105
	v_cvt_pk_bf16_f32 v223, v106, v107
	v_cvt_pk_bf16_f32 v224, v108, v109
	v_cvt_pk_bf16_f32 v225, v110, v111
	v_add_f32_e32 v197, v197, v234
	v_add_f32_e32 v197, v197, v235
	ds_read_b128 v[152:155], v0 offset:36928
	ds_read_b128 v[10:13], v0 offset:41536
	ds_read_b128 v[6:9], v0 offset:46144
	ds_read_b128 v[2:5], v0 offset:50752
	s_waitcnt lgkmcnt(7)
	v_mfma_f32_32x32x16_bf16 v[64:79], v[198:201], v[222:225], v[64:79]
	v_sub_f32_e32 v80, v80, v194
	v_sub_f32_e32 v81, v81, v194
	v_sub_f32_e32 v82, v82, v194
	v_sub_f32_e32 v83, v83, v194
	v_sub_f32_e32 v84, v84, v194
	v_sub_f32_e32 v85, v85, v194
	v_sub_f32_e32 v86, v86, v194
	s_waitcnt lgkmcnt(6)
	v_mfma_f32_32x32x16_bf16 v[48:63], v[202:205], v[222:225], v[48:63]
	v_sub_f32_e32 v87, v87, v194
	v_exp_f32_e32 v80, v80
	v_exp_f32_e32 v81, v81
	v_exp_f32_e32 v82, v82
	v_exp_f32_e32 v83, v83
	v_exp_f32_e32 v84, v84
	v_exp_f32_e32 v85, v85
	s_waitcnt lgkmcnt(5)
	v_mfma_f32_32x32x16_bf16 v[32:47], v[206:209], v[222:225], v[32:47]
	v_exp_f32_e32 v86, v86
	v_exp_f32_e32 v87, v87
	v_add_f32_e32 v234, v80, v81
	v_add_f32_e32 v235, v82, v83
	v_add_f32_e32 v234, v234, v84
	v_add_f32_e32 v235, v235, v85
	v_add_f32_e32 v234, v234, v86
	s_waitcnt lgkmcnt(4)
	v_mfma_f32_32x32x16_bf16 v[16:31], v[210:213], v[222:225], v[16:31]
	v_add_f32_e32 v235, v235, v87
	v_cvt_pk_bf16_f32 v226, v80, v81
	v_cvt_pk_bf16_f32 v227, v82, v83
	v_cvt_pk_bf16_f32 v228, v84, v85
	v_cvt_pk_bf16_f32 v229, v86, v87
	v_add_f32_e32 v197, v197, v234
	v_add_f32_e32 v197, v197, v235
	ds_read_b128 v[198:201], v0 offset:36960
	ds_read_b128 v[202:205], v0 offset:41568
	ds_read_b128 v[206:209], v0 offset:46176
	ds_read_b128 v[210:213], v0 offset:50784
	s_waitcnt lgkmcnt(7)
	v_mfma_f32_32x32x16_bf16 v[64:79], v[152:155], v[226:229], v[64:79]
	v_sub_f32_e32 v88, v88, v194
	v_sub_f32_e32 v89, v89, v194
	v_sub_f32_e32 v90, v90, v194
	v_sub_f32_e32 v91, v91, v194
	v_sub_f32_e32 v92, v92, v194
	v_sub_f32_e32 v93, v93, v194
	v_sub_f32_e32 v94, v94, v194
	s_waitcnt lgkmcnt(6)
	v_mfma_f32_32x32x16_bf16 v[48:63], v[10:13], v[226:229], v[48:63]
	v_sub_f32_e32 v95, v95, v194
	v_exp_f32_e32 v88, v88
	v_exp_f32_e32 v89, v89
	v_exp_f32_e32 v90, v90
	v_exp_f32_e32 v91, v91
	v_exp_f32_e32 v92, v92
	v_exp_f32_e32 v93, v93
	s_waitcnt lgkmcnt(5)
	v_mfma_f32_32x32x16_bf16 v[32:47], v[6:9], v[226:229], v[32:47]
	v_exp_f32_e32 v94, v94
	v_exp_f32_e32 v95, v95
	v_add_f32_e32 v234, v88, v89
	v_add_f32_e32 v235, v90, v91
	v_add_f32_e32 v234, v234, v92
	v_add_f32_e32 v235, v235, v93
	v_add_f32_e32 v234, v234, v94
	s_waitcnt lgkmcnt(4)
	v_mfma_f32_32x32x16_bf16 v[16:31], v[2:5], v[226:229], v[16:31]
	v_add_f32_e32 v235, v235, v95
	v_cvt_pk_bf16_f32 v230, v88, v89
	v_cvt_pk_bf16_f32 v231, v90, v91
	v_cvt_pk_bf16_f32 v232, v92, v93
	v_cvt_pk_bf16_f32 v233, v94, v95
	v_add_f32_e32 v197, v197, v234
	v_add_f32_e32 v197, v197, v235
	s_waitcnt lgkmcnt(3)
	v_mfma_f32_32x32x16_bf16 v[64:79], v[198:201], v[230:233], v[64:79]
	s_waitcnt lgkmcnt(2)
	v_mfma_f32_32x32x16_bf16 v[48:63], v[202:205], v[230:233], v[48:63]
	s_waitcnt lgkmcnt(1)
	v_mfma_f32_32x32x16_bf16 v[32:47], v[206:209], v[230:233], v[32:47]
	s_waitcnt lgkmcnt(0)
	v_mfma_f32_32x32x16_bf16 v[16:31], v[210:213], v[230:233], v[16:31]
	s_cmp_gt_u32 s2, s39
	s_cbranch_scc0 .LBB0_123
	s_branch .LBB0_124

; __device__ __forceinline__ void scan_phase(const Args& a, LAS unsigned char* lds, const bf16* Z, const float* W, const bf16* Aa, const bf16* KK, float* Y, int tid, int lane, int wave) {
;     ...
;                 const LAS float* sb = buf + (ch & 1) * (SCH * SROW) + 4 * j;
;                 const LAS float* vb = buf + (ch & 1) * (SCH * SROW) + 320 + ri;
;                 f32x4 pw[3], pk[3], pa[3], pb[3], pr[3]; float pv[3];
; #pragma unroll
;                 for (int i = 0; i < 2; ++i) { const LAS float* p = sb + i * SROW;
;                     pw[i] = *(const LAS f32x4*)p; pk[i] = *(const LAS f32x4*)(p + 64); pa[i] = *(const LAS f32x4*)(p + 128); pb[i] = *(const LAS f32x4*)(p + 192); pr[i] = *(const LAS f32x4*)(p + 256); pv[i] = vb[i * SROW]; }
;                 float ykA = 0.f, ykB = 0.f, yd = 0.f;
; #pragma unroll
;                 for (int q = 0; q < SCH; ++q) {
;                     const f32x4 wv = pw[q % 3], kv = pk[q % 3], av = pa[q % 3], bv = pb[q % 3], rv = pr[q % 3]; const float vv = pv[q % 3];
;                     if (q + 2 < SCH) {
;                         const LAS float* p = sb + (q + 2) * SROW; const int i = (q + 2) % 3;
;                         pw[i] = *(const LAS f32x4*)p; pk[i] = *(const LAS f32x4*)(p + 64); pa[i] = *(const LAS f32x4*)(p + 128); pb[i] = *(const LAS f32x4*)(p + 192); pr[i] = *(const LAS f32x4*)(p + 256);
;                         pv[i] = vb[(q + 2) * SROW];
;                     }
;                     f32x2 t2 = S01 * (f32x2){av.x, av.y}; t2 = S23 * (f32x2){av.z, av.w} + t2;
;                     float sa = t2.x + t2.y;
;                     sa += dppf<0xB1>(sa); yd += dppf<0xB1>(yd);
;                     sa += dppf<0x4E>(sa); yd += dppf<0x4E>(yd);
;                     sa += dppf<0x141>(sa); yd += dppf<0x141>(yd);
;                     sa += dppf<0x140>(sa); yd += dppf<0x140>(yd);
;                     if (q > 0) { if (q <= 16) ykA = (j == q - 1) ? yd : ykA; else ykB = (j == q - 17) ? yd : ykB; }
;                     const f32x2 u01 = S01 * (f32x2){wv.x, wv.y} + (f32x2){kv.x, kv.y} * vv, u23 = S23 * (f32x2){wv.z, wv.w} + (f32x2){kv.z, kv.w} * vv;
;                     S01 = u01 + (f32x2){bv.x, bv.y} * sa; S23 = u23 + (f32x2){bv.z, bv.w} * sa;
;                     f32x2 y2 = S01 * (f32x2){rv.x, rv.y}; y2 = S23 * (f32x2){rv.z, rv.w} + y2;
;                     yd = y2.x + y2.y;
;                 }
.LBB0_283:
	s_andn2_b64 vcc, exec, s[12:13]
	s_cbranch_vccnz .LBB0_224
	s_bitcmp1_b32 s22, 0
	s_cselect_b32 s16, 0xa800, 0
	s_add_i32 s16, s16, 0
	v_add_u32_e32 v195, s16, v123
	v_lshl_add_u32 v127, v126, 2, s16
	ds_read_b128 v[64:67], v195
	ds_read_b128 v[68:71], v195 offset:256
	ds_read_b128 v[72:75], v195 offset:512
	ds_read_b128 v[76:79], v195 offset:768
	ds_read_b128 v[80:83], v195 offset:1024
	ds_read_b32 v62, v127 offset:1280
	ds_read_b128 v[84:87], v195 offset:1344
	ds_read_b128 v[88:91], v195 offset:1600
	ds_read_b128 v[92:95], v195 offset:1856
	ds_read_b128 v[96:99], v195 offset:2112
	ds_read_b128 v[100:103], v195 offset:2368
	ds_read_b32 v63, v127 offset:2624
	s_waitcnt lgkmcnt(6)
	v_mul_f32_e32 v204, v58, v72
	v_mul_f32_e32 v205, v59, v73
	v_fmac_f32_e32 v204, v60, v74
	v_fmac_f32_e32 v205, v61, v75
	v_add_f32_e32 v204, v204, v205
	ds_read_b128 v[104:107], v195 offset:2688
	ds_read_b128 v[108:111], v195 offset:2944
	ds_read_b128 v[112:115], v195 offset:3200
	ds_read_b128 v[196:199], v195 offset:3456
	ds_read_b128 v[200:203], v195 offset:3712
	ds_read_b32 v182, v127 offset:3968
	v_mul_f32_e32 v208, v58, v64
	v_mul_f32_e32 v209, v59, v65
	v_add_f32_dpp v204, v204, v204 quad_perm:[1,0,3,2] row_mask:0xf bank_mask:0xf bound_ctrl:1
	v_mul_f32_e32 v210, v60, v66
	v_mul_f32_e32 v211, v61, v67
	v_add_f32_dpp v204, v204, v204 quad_perm:[2,3,0,1] row_mask:0xf bank_mask:0xf bound_ctrl:1
	v_fmac_f32_e32 v208, v68, v62
	v_fmac_f32_e32 v209, v69, v62
	v_add_f32_dpp v204, v204, v204 row_half_mirror row_mask:0xf bank_mask:0xf bound_ctrl:1
	v_fmac_f32_e32 v210, v70, v62
	v_fmac_f32_e32 v211, v71, v62
	v_add_f32_dpp v204, v204, v204 row_mirror row_mask:0xf bank_mask:0xf bound_ctrl:1
	v_fma_f32 v58, v76, v204, v208
	v_fma_f32 v59, v77, v204, v209
	v_fma_f32 v60, v78, v204, v210
	v_fma_f32 v61, v79, v204, v211
	s_waitcnt lgkmcnt(6)
	v_mul_f32_e32 v212, v58, v80
	v_mul_f32_e32 v213, v59, v81
	v_mul_f32_e32 v204, v58, v92
	v_mul_f32_e32 v205, v59, v93
	v_fmac_f32_e32 v212, v60, v82
	v_fmac_f32_e32 v213, v61, v83
	v_fmac_f32_e32 v204, v60, v94
	v_fmac_f32_e32 v205, v61, v95
	v_add_f32_e32 v212, v212, v213
	v_add_f32_e32 v204, v204, v205
	ds_read_b128 v[64:67], v195 offset:4032
	ds_read_b128 v[68:71], v195 offset:4288
	ds_read_b128 v[72:75], v195 offset:4544
	ds_read_b128 v[76:79], v195 offset:4800
	ds_read_b128 v[80:83], v195 offset:5056
	ds_read_b32 v62, v127 offset:5312
	v_mul_f32_e32 v208, v58, v84
	v_mul_f32_e32 v209, v59, v85
	v_add_f32_dpp v204, v204, v204 quad_perm:[1,0,3,2] row_mask:0xf bank_mask:0xf bound_ctrl:1
	v_add_f32_dpp v212, v212, v212 quad_perm:[1,0,3,2] row_mask:0xf bank_mask:0xf bound_ctrl:1
	v_mul_f32_e32 v210, v60, v86
	v_add_f32_dpp v204, v204, v204 quad_perm:[2,3,0,1] row_mask:0xf bank_mask:0xf bound_ctrl:1
	v_add_f32_dpp v212, v212, v212 quad_perm:[2,3,0,1] row_mask:0xf bank_mask:0xf bound_ctrl:1
	v_mul_f32_e32 v211, v61, v87
	v_add_f32_dpp v204, v204, v204 row_half_mirror row_mask:0xf bank_mask:0xf bound_ctrl:1
	v_add_f32_dpp v212, v212, v212 row_half_mirror row_mask:0xf bank_mask:0xf bound_ctrl:1
	v_fmac_f32_e32 v208, v88, v63
	v_add_f32_dpp v204, v204, v204 row_mirror row_mask:0xf bank_mask:0xf bound_ctrl:1
	v_add_f32_dpp v212, v212, v212 row_mirror row_mask:0xf bank_mask:0xf bound_ctrl:1
	v_fmac_f32_e32 v209, v89, v63
	v_fmac_f32_e32 v210, v90, v63
	v_fmac_f32_e32 v211, v91, v63
	v_cndmask_b32_e64 v214, 0, v212, s[82:83]
	v_fma_f32 v58, v96, v204, v208
	v_fma_f32 v59, v97, v204, v209
	v_fma_f32 v60, v98, v204, v210
	v_fma_f32 v61, v99, v204, v211
	s_waitcnt lgkmcnt(6)
	v_mul_f32_e32 v212, v58, v100
	v_mul_f32_e32 v213, v59, v101
	v_mul_f32_e32 v204, v58, v112
	v_mul_f32_e32 v205, v59, v113
	v_fmac_f32_e32 v212, v60, v102
	v_fmac_f32_e32 v213, v61, v103
	v_fmac_f32_e32 v204, v60, v114
	v_fmac_f32_e32 v205, v61, v115
	v_add_f32_e32 v212, v212, v213
	v_add_f32_e32 v204, v204, v205
	ds_read_b128 v[84:87], v195 offset:5376
	ds_read_b128 v[88:91], v195 offset:5632
	ds_read_b128 v[92:95], v195 offset:5888
	ds_read_b128 v[96:99], v195 offset:6144
	ds_read_b128 v[100:103], v195 offset:6400
	ds_read_b32 v63, v127 offset:6656
	v_mul_f32_e32 v208, v58, v104
	v_mul_f32_e32 v209, v59, v105
	v_add_f32_dpp v204, v204, v204 quad_perm:[1,0,3,2] row_mask:0xf bank_mask:0xf bound_ctrl:1
	v_add_f32_dpp v212, v212, v212 quad_perm:[1,0,3,2] row_mask:0xf bank_mask:0xf bound_ctrl:1
	v_mul_f32_e32 v210, v60, v106
	v_add_f32_dpp v204, v204, v204 quad_perm:[2,3,0,1] row_mask:0xf bank_mask:0xf bound_ctrl:1
	v_add_f32_dpp v212, v212, v212 quad_perm:[2,3,0,1] row_mask:0xf bank_mask:0xf bound_ctrl:1
	v_mul_f32_e32 v211, v61, v107
	v_add_f32_dpp v204, v204, v204 row_half_mirror row_mask:0xf bank_mask:0xf bound_ctrl:1
	v_add_f32_dpp v212, v212, v212 row_half_mirror row_mask:0xf bank_mask:0xf bound_ctrl:1
	v_fmac_f32_e32 v208, v108, v182
	v_add_f32_dpp v204, v204, v204 row_mirror row_mask:0xf bank_mask:0xf bound_ctrl:1
	v_add_f32_dpp v212, v212, v212 row_mirror row_mask:0xf bank_mask:0xf bound_ctrl:1
	v_fmac_f32_e32 v209, v109, v182
	v_fmac_f32_e32 v210, v110, v182
	v_fmac_f32_e32 v211, v111, v182
	v_cndmask_b32_e64 v214, v214, v212, s[80:81]
	v_fma_f32 v58, v196, v204, v208
	v_fma_f32 v59, v197, v204, v209
	v_fma_f32 v60, v198, v204, v210
	v_fma_f32 v61, v199, v204, v211
	s_waitcnt lgkmcnt(6)
; #define LAS __attribute__((address_space(3)))
; template <int CTRL> __device__ __forceinline__ float dppf(float v) { return __int_as_float(__builtin_amdgcn_update_dpp(0, __float_as_int(v), CTRL, 0xf, 0xf, true)); }
; __device__ __forceinline__ void scan_phase(const Args& a, LAS unsigned char* lds, const bf16* Z, const float* W, const bf16* Aa, const bf16* KK, float* Y, int tid, int lane, int wave) {
;     ...
;                 for (int q = 0; q < SCH; ++q) {
;                     const f32x4 wv = pw[q % 3], kv = pk[q % 3], av = pa[q % 3], bv = pb[q % 3], rv = pr[q % 3]; const float vv = pv[q % 3];
;                     if (q + 2 < SCH) {
;                         const LAS float* p = sb + (q + 2) * SROW; const int i = (q + 2) % 3;
;                         pw[i] = *(const LAS f32x4*)p; pk[i] = *(const LAS f32x4*)(p + 64); pa[i] = *(const LAS f32x4*)(p + 128); pb[i] = *(const LAS f32x4*)(p + 192); pr[i] = *(const LAS f32x4*)(p + 256);
;                         pv[i] = vb[(q + 2) * SROW];
;                     }
;                     f32x2 t2 = S01 * (f32x2){av.x, av.y}; t2 = S23 * (f32x2){av.z, av.w} + t2;
;                     float sa = t2.x + t2.y;
;                     sa += dppf<0xB1>(sa); yd += dppf<0xB1>(yd);
;                     sa += dppf<0x4E>(sa); yd += dppf<0x4E>(yd);
;                     sa += dppf<0x141>(sa); yd += dppf<0x141>(yd);
;                     sa += dppf<0x140>(sa); yd += dppf<0x140>(yd);
;                     if (q > 0) { if (q <= 16) ykA = (j == q - 1) ? yd : ykA; else ykB = (j == q - 17) ? yd : ykB; }
;                     const f32x2 u01 = S01 * (f32x2){wv.x, wv.y} + (f32x2){kv.x, kv.y} * vv, u23 = S23 * (f32x2){wv.z, wv.w} + (f32x2){kv.z, kv.w} * vv;
;                     S01 = u01 + (f32x2){bv.x, bv.y} * sa; S23 = u23 + (f32x2){bv.z, bv.w} * sa;
;                     f32x2 y2 = S01 * (f32x2){rv.x, rv.y}; y2 = S23 * (f32x2){rv.z, rv.w} + y2;
;                     yd = y2.x + y2.y;
;                 }
	v_mul_f32_e32 v212, v58, v200
	v_mul_f32_e32 v213, v59, v201
	v_mul_f32_e32 v204, v58, v72
	v_mul_f32_e32 v205, v59, v73
	v_fmac_f32_e32 v212, v60, v202
	v_fmac_f32_e32 v213, v61, v203
	v_fmac_f32_e32 v204, v60, v74
	v_fmac_f32_e32 v205, v61, v75
	v_add_f32_e32 v212, v212, v213
	v_add_f32_e32 v204, v204, v205
	ds_read_b128 v[104:107], v195 offset:6720
	ds_read_b128 v[108:111], v195 offset:6976
	ds_read_b128 v[112:115], v195 offset:7232
	ds_read_b128 v[196:199], v195 offset:7488
	ds_read_b128 v[200:203], v195 offset:7744
	ds_read_b32 v182, v127 offset:8000
	v_mul_f32_e32 v208, v58, v64
	v_mul_f32_e32 v209, v59, v65
	v_add_f32_dpp v204, v204, v204 quad_perm:[1,0,3,2] row_mask:0xf bank_mask:0xf bound_ctrl:1
	v_add_f32_dpp v212, v212, v212 quad_perm:[1,0,3,2] row_mask:0xf bank_mask:0xf bound_ctrl:1
	v_mul_f32_e32 v210, v60, v66
	v_add_f32_dpp v204, v204, v204 quad_perm:[2,3,0,1] row_mask:0xf bank_mask:0xf bound_ctrl:1
	v_add_f32_dpp v212, v212, v212 quad_perm:[2,3,0,1] row_mask:0xf bank_mask:0xf bound_ctrl:1
	v_mul_f32_e32 v211, v61, v67
	v_add_f32_dpp v204, v204, v204 row_half_mirror row_mask:0xf bank_mask:0xf bound_ctrl:1
	v_add_f32_dpp v212, v212, v212 row_half_mirror row_mask:0xf bank_mask:0xf bound_ctrl:1
	v_fmac_f32_e32 v208, v68, v62
	v_add_f32_dpp v204, v204, v204 row_mirror row_mask:0xf bank_mask:0xf bound_ctrl:1
	v_add_f32_dpp v212, v212, v212 row_mirror row_mask:0xf bank_mask:0xf bound_ctrl:1
	v_fmac_f32_e32 v209, v69, v62
	v_fmac_f32_e32 v210, v70, v62
	v_fmac_f32_e32 v211, v71, v62
	v_cndmask_b32_e64 v214, v214, v212, s[6:7]
	v_fma_f32 v58, v76, v204, v208
	v_fma_f32 v59, v77, v204, v209
	v_fma_f32 v60, v78, v204, v210
	v_fma_f32 v61, v79, v204, v211
	s_waitcnt lgkmcnt(6)
	v_mul_f32_e32 v212, v58, v80
	v_mul_f32_e32 v213, v59, v81
	v_mul_f32_e32 v204, v58, v92
	v_mul_f32_e32 v205, v59, v93
	v_fmac_f32_e32 v212, v60, v82
	v_fmac_f32_e32 v213, v61, v83
	v_fmac_f32_e32 v204, v60, v94
	v_fmac_f32_e32 v205, v61, v95
	v_add_f32_e32 v212, v212, v213
	v_add_f32_e32 v204, v204, v205
	ds_read_b128 v[64:67], v195 offset:8064
	ds_read_b128 v[68:71], v195 offset:8320
	ds_read_b128 v[72:75], v195 offset:8576
	ds_read_b128 v[76:79], v195 offset:8832
	ds_read_b128 v[80:83], v195 offset:9088
	ds_read_b32 v62, v127 offset:9344
	v_mul_f32_e32 v208, v58, v84
	v_mul_f32_e32 v209, v59, v85
	v_add_f32_dpp v204, v204, v204 quad_perm:[1,0,3,2] row_mask:0xf bank_mask:0xf bound_ctrl:1
	v_add_f32_dpp v212, v212, v212 quad_perm:[1,0,3,2] row_mask:0xf bank_mask:0xf bound_ctrl:1
	v_mul_f32_e32 v210, v60, v86
	v_add_f32_dpp v204, v204, v204 quad_perm:[2,3,0,1] row_mask:0xf bank_mask:0xf bound_ctrl:1
	v_add_f32_dpp v212, v212, v212 quad_perm:[2,3,0,1] row_mask:0xf bank_mask:0xf bound_ctrl:1
	v_mul_f32_e32 v211, v61, v87
	v_add_f32_dpp v204, v204, v204 row_half_mirror row_mask:0xf bank_mask:0xf bound_ctrl:1
	v_add_f32_dpp v212, v212, v212 row_half_mirror row_mask:0xf bank_mask:0xf bound_ctrl:1
	v_fmac_f32_e32 v208, v88, v63
	v_add_f32_dpp v204, v204, v204 row_mirror row_mask:0xf bank_mask:0xf bound_ctrl:1
	v_add_f32_dpp v212, v212, v212 row_mirror row_mask:0xf bank_mask:0xf bound_ctrl:1
	v_fmac_f32_e32 v209, v89, v63
	v_fmac_f32_e32 v210, v90, v63
	v_fmac_f32_e32 v211, v91, v63
	v_cndmask_b32_e64 v214, v214, v212, s[8:9]
	v_fma_f32 v58, v96, v204, v208
	v_fma_f32 v59, v97, v204, v209
	v_fma_f32 v60, v98, v204, v210
	v_fma_f32 v61, v99, v204, v211
	s_waitcnt lgkmcnt(6)
	v_mul_f32_e32 v212, v58, v100
	v_mul_f32_e32 v213, v59, v101
	v_mul_f32_e32 v204, v58, v112
	v_mul_f32_e32 v205, v59, v113
	v_fmac_f32_e32 v212, v60, v102
	v_fmac_f32_e32 v213, v61, v103
	v_fmac_f32_e32 v204, v60, v114
	v_fmac_f32_e32 v205, v61, v115
	v_add_f32_e32 v212, v212, v213
	v_add_f32_e32 v204, v204, v205
	ds_read_b128 v[84:87], v195 offset:9408
	ds_read_b128 v[88:91], v195 offset:9664
	ds_read_b128 v[92:95], v195 offset:9920
	ds_read_b128 v[96:99], v195 offset:10176
	ds_read_b128 v[100:103], v195 offset:10432
	ds_read_b32 v63, v127 offset:10688
	v_mul_f32_e32 v208, v58, v104
	v_mul_f32_e32 v209, v59, v105
	v_add_f32_dpp v204, v204, v204 quad_perm:[1,0,3,2] row_mask:0xf bank_mask:0xf bound_ctrl:1
	v_add_f32_dpp v212, v212, v212 quad_perm:[1,0,3,2] row_mask:0xf bank_mask:0xf bound_ctrl:1
	v_mul_f32_e32 v210, v60, v106
	v_add_f32_dpp v204, v204, v204 quad_perm:[2,3,0,1] row_mask:0xf bank_mask:0xf bound_ctrl:1
	v_add_f32_dpp v212, v212, v212 quad_perm:[2,3,0,1] row_mask:0xf bank_mask:0xf bound_ctrl:1
	v_mul_f32_e32 v211, v61, v107
	v_add_f32_dpp v204, v204, v204 row_half_mirror row_mask:0xf bank_mask:0xf bound_ctrl:1
	v_add_f32_dpp v212, v212, v212 row_half_mirror row_mask:0xf bank_mask:0xf bound_ctrl:1
	v_fmac_f32_e32 v208, v108, v182
	v_add_f32_dpp v204, v204, v204 row_mirror row_mask:0xf bank_mask:0xf bound_ctrl:1
	v_add_f32_dpp v212, v212, v212 row_mirror row_mask:0xf bank_mask:0xf bound_ctrl:1
	v_fmac_f32_e32 v209, v109, v182
	v_fmac_f32_e32 v210, v110, v182
	v_fmac_f32_e32 v211, v111, v182
	v_cndmask_b32_e64 v214, v214, v212, s[10:11]
	v_fma_f32 v58, v196, v204, v208
	v_fma_f32 v59, v197, v204, v209
	v_fma_f32 v60, v198, v204, v210
	v_fma_f32 v61, v199, v204, v211
	s_waitcnt lgkmcnt(6)
; #define LAS __attribute__((address_space(3)))
; template <int CTRL> __device__ __forceinline__ float dppf(float v) { return __int_as_float(__builtin_amdgcn_update_dpp(0, __float_as_int(v), CTRL, 0xf, 0xf, true)); }
; __device__ __forceinline__ void scan_phase(const Args& a, LAS unsigned char* lds, const bf16* Z, const float* W, const bf16* Aa, const bf16* KK, float* Y, int tid, int lane, int wave) {
;     ...
;                 for (int q = 0; q < SCH; ++q) {
;                     const f32x4 wv = pw[q % 3], kv = pk[q % 3], av = pa[q % 3], bv = pb[q % 3], rv = pr[q % 3]; const float vv = pv[q % 3];
;                     if (q + 2 < SCH) {
;                         const LAS float* p = sb + (q + 2) * SROW; const int i = (q + 2) % 3;
;                         pw[i] = *(const LAS f32x4*)p; pk[i] = *(const LAS f32x4*)(p + 64); pa[i] = *(const LAS f32x4*)(p + 128); pb[i] = *(const LAS f32x4*)(p + 192); pr[i] = *(const LAS f32x4*)(p + 256);
;                         pv[i] = vb[(q + 2) * SROW];
;                     }
;                     f32x2 t2 = S01 * (f32x2){av.x, av.y}; t2 = S23 * (f32x2){av.z, av.w} + t2;
;                     float sa = t2.x + t2.y;
;                     sa += dppf<0xB1>(sa); yd += dppf<0xB1>(yd);
;                     sa += dppf<0x4E>(sa); yd += dppf<0x4E>(yd);
;                     sa += dppf<0x141>(sa); yd += dppf<0x141>(yd);
;                     sa += dppf<0x140>(sa); yd += dppf<0x140>(yd);
;                     if (q > 0) { if (q <= 16) ykA = (j == q - 1) ? yd : ykA; else ykB = (j == q - 17) ? yd : ykB; }
;                     const f32x2 u01 = S01 * (f32x2){wv.x, wv.y} + (f32x2){kv.x, kv.y} * vv, u23 = S23 * (f32x2){wv.z, wv.w} + (f32x2){kv.z, kv.w} * vv;
;                     S01 = u01 + (f32x2){bv.x, bv.y} * sa; S23 = u23 + (f32x2){bv.z, bv.w} * sa;
;                     f32x2 y2 = S01 * (f32x2){rv.x, rv.y}; y2 = S23 * (f32x2){rv.z, rv.w} + y2;
;                     yd = y2.x + y2.y;
;                 }
	v_mul_f32_e32 v212, v58, v200
	v_mul_f32_e32 v213, v59, v201
	v_mul_f32_e32 v204, v58, v72
	v_mul_f32_e32 v205, v59, v73
	v_fmac_f32_e32 v212, v60, v202
	v_fmac_f32_e32 v213, v61, v203
	v_fmac_f32_e32 v204, v60, v74
	v_fmac_f32_e32 v205, v61, v75
	v_add_f32_e32 v212, v212, v213
	v_add_f32_e32 v204, v204, v205
	ds_read_b128 v[104:107], v195 offset:10752
	ds_read_b128 v[108:111], v195 offset:11008
	ds_read_b128 v[112:115], v195 offset:11264
	ds_read_b128 v[196:199], v195 offset:11520
	ds_read_b128 v[200:203], v195 offset:11776
	ds_read_b32 v182, v127 offset:12032
	v_mul_f32_e32 v208, v58, v64
	v_mul_f32_e32 v209, v59, v65
	v_add_f32_dpp v204, v204, v204 quad_perm:[1,0,3,2] row_mask:0xf bank_mask:0xf bound_ctrl:1
	v_add_f32_dpp v212, v212, v212 quad_perm:[1,0,3,2] row_mask:0xf bank_mask:0xf bound_ctrl:1
	v_mul_f32_e32 v210, v60, v66
	v_add_f32_dpp v204, v204, v204 quad_perm:[2,3,0,1] row_mask:0xf bank_mask:0xf bound_ctrl:1
	v_add_f32_dpp v212, v212, v212 quad_perm:[2,3,0,1] row_mask:0xf bank_mask:0xf bound_ctrl:1
	v_mul_f32_e32 v211, v61, v67
	v_add_f32_dpp v204, v204, v204 row_half_mirror row_mask:0xf bank_mask:0xf bound_ctrl:1
	v_add_f32_dpp v212, v212, v212 row_half_mirror row_mask:0xf bank_mask:0xf bound_ctrl:1
	v_fmac_f32_e32 v208, v68, v62
	v_add_f32_dpp v204, v204, v204 row_mirror row_mask:0xf bank_mask:0xf bound_ctrl:1
	v_add_f32_dpp v212, v212, v212 row_mirror row_mask:0xf bank_mask:0xf bound_ctrl:1
	v_fmac_f32_e32 v209, v69, v62
	v_fmac_f32_e32 v210, v70, v62
	v_fmac_f32_e32 v211, v71, v62
	v_cndmask_b32_e64 v214, v214, v212, s[90:91]
	v_fma_f32 v58, v76, v204, v208
	v_fma_f32 v59, v77, v204, v209
	v_fma_f32 v60, v78, v204, v210
	v_fma_f32 v61, v79, v204, v211
	s_waitcnt lgkmcnt(6)
	v_mul_f32_e32 v212, v58, v80
	v_mul_f32_e32 v213, v59, v81
	v_mul_f32_e32 v204, v58, v92
	v_mul_f32_e32 v205, v59, v93
	v_fmac_f32_e32 v212, v60, v82
	v_fmac_f32_e32 v213, v61, v83
	v_fmac_f32_e32 v204, v60, v94
	v_fmac_f32_e32 v205, v61, v95
	v_add_f32_e32 v212, v212, v213
	v_add_f32_e32 v204, v204, v205
	ds_read_b128 v[64:67], v195 offset:12096
	ds_read_b128 v[68:71], v195 offset:12352
	ds_read_b128 v[72:75], v195 offset:12608
	ds_read_b128 v[76:79], v195 offset:12864
	ds_read_b128 v[80:83], v195 offset:13120
	ds_read_b32 v62, v127 offset:13376
	v_mul_f32_e32 v208, v58, v84
	v_mul_f32_e32 v209, v59, v85
	v_add_f32_dpp v204, v204, v204 quad_perm:[1,0,3,2] row_mask:0xf bank_mask:0xf bound_ctrl:1
	v_add_f32_dpp v212, v212, v212 quad_perm:[1,0,3,2] row_mask:0xf bank_mask:0xf bound_ctrl:1
	v_mul_f32_e32 v210, v60, v86
	v_add_f32_dpp v204, v204, v204 quad_perm:[2,3,0,1] row_mask:0xf bank_mask:0xf bound_ctrl:1
	v_add_f32_dpp v212, v212, v212 quad_perm:[2,3,0,1] row_mask:0xf bank_mask:0xf bound_ctrl:1
	v_mul_f32_e32 v211, v61, v87
	v_add_f32_dpp v204, v204, v204 row_half_mirror row_mask:0xf bank_mask:0xf bound_ctrl:1
	v_add_f32_dpp v212, v212, v212 row_half_mirror row_mask:0xf bank_mask:0xf bound_ctrl:1
	v_fmac_f32_e32 v208, v88, v63
	v_add_f32_dpp v204, v204, v204 row_mirror row_mask:0xf bank_mask:0xf bound_ctrl:1
	v_add_f32_dpp v212, v212, v212 row_mirror row_mask:0xf bank_mask:0xf bound_ctrl:1
	v_fmac_f32_e32 v209, v89, v63
	v_fmac_f32_e32 v210, v90, v63
	v_fmac_f32_e32 v211, v91, v63
	v_cndmask_b32_e64 v214, v214, v212, s[60:61]
	v_fma_f32 v58, v96, v204, v208
	v_fma_f32 v59, v97, v204, v209
	v_fma_f32 v60, v98, v204, v210
	v_fma_f32 v61, v99, v204, v211
	s_waitcnt lgkmcnt(6)
	v_mul_f32_e32 v212, v58, v100
	v_mul_f32_e32 v213, v59, v101
	v_mul_f32_e32 v204, v58, v112
	v_mul_f32_e32 v205, v59, v113
	v_fmac_f32_e32 v212, v60, v102
	v_fmac_f32_e32 v213, v61, v103
	v_fmac_f32_e32 v204, v60, v114
	v_fmac_f32_e32 v205, v61, v115
	v_add_f32_e32 v212, v212, v213
	v_add_f32_e32 v204, v204, v205
	ds_read_b128 v[84:87], v195 offset:13440
	ds_read_b128 v[88:91], v195 offset:13696
	ds_read_b128 v[92:95], v195 offset:13952
	ds_read_b128 v[96:99], v195 offset:14208
	ds_read_b128 v[100:103], v195 offset:14464
	ds_read_b32 v63, v127 offset:14720
	v_mul_f32_e32 v208, v58, v104
	v_mul_f32_e32 v209, v59, v105
	v_add_f32_dpp v204, v204, v204 quad_perm:[1,0,3,2] row_mask:0xf bank_mask:0xf bound_ctrl:1
	v_add_f32_dpp v212, v212, v212 quad_perm:[1,0,3,2] row_mask:0xf bank_mask:0xf bound_ctrl:1
	v_mul_f32_e32 v210, v60, v106
	v_add_f32_dpp v204, v204, v204 quad_perm:[2,3,0,1] row_mask:0xf bank_mask:0xf bound_ctrl:1
	v_add_f32_dpp v212, v212, v212 quad_perm:[2,3,0,1] row_mask:0xf bank_mask:0xf bound_ctrl:1
	v_mul_f32_e32 v211, v61, v107
	v_add_f32_dpp v204, v204, v204 row_half_mirror row_mask:0xf bank_mask:0xf bound_ctrl:1
	v_add_f32_dpp v212, v212, v212 row_half_mirror row_mask:0xf bank_mask:0xf bound_ctrl:1
	v_fmac_f32_e32 v208, v108, v182
	v_add_f32_dpp v204, v204, v204 row_mirror row_mask:0xf bank_mask:0xf bound_ctrl:1
	v_add_f32_dpp v212, v212, v212 row_mirror row_mask:0xf bank_mask:0xf bound_ctrl:1
	v_fmac_f32_e32 v209, v109, v182
	v_fmac_f32_e32 v210, v110, v182
	v_fmac_f32_e32 v211, v111, v182
	v_cndmask_b32_e64 v214, v214, v212, s[62:63]
	v_fma_f32 v58, v196, v204, v208
	v_fma_f32 v59, v197, v204, v209
	v_fma_f32 v60, v198, v204, v210
	v_fma_f32 v61, v199, v204, v211
	s_waitcnt lgkmcnt(6)
; #define LAS __attribute__((address_space(3)))
; template <int CTRL> __device__ __forceinline__ float dppf(float v) { return __int_as_float(__builtin_amdgcn_update_dpp(0, __float_as_int(v), CTRL, 0xf, 0xf, true)); }
; __device__ __forceinline__ void scan_phase(const Args& a, LAS unsigned char* lds, const bf16* Z, const float* W, const bf16* Aa, const bf16* KK, float* Y, int tid, int lane, int wave) {
;     ...
;                 for (int q = 0; q < SCH; ++q) {
;                     const f32x4 wv = pw[q % 3], kv = pk[q % 3], av = pa[q % 3], bv = pb[q % 3], rv = pr[q % 3]; const float vv = pv[q % 3];
;                     if (q + 2 < SCH) {
;                         const LAS float* p = sb + (q + 2) * SROW; const int i = (q + 2) % 3;
;                         pw[i] = *(const LAS f32x4*)p; pk[i] = *(const LAS f32x4*)(p + 64); pa[i] = *(const LAS f32x4*)(p + 128); pb[i] = *(const LAS f32x4*)(p + 192); pr[i] = *(const LAS f32x4*)(p + 256);
;                         pv[i] = vb[(q + 2) * SROW];
;                     }
;                     f32x2 t2 = S01 * (f32x2){av.x, av.y}; t2 = S23 * (f32x2){av.z, av.w} + t2;
;                     float sa = t2.x + t2.y;
;                     sa += dppf<0xB1>(sa); yd += dppf<0xB1>(yd);
;                     sa += dppf<0x4E>(sa); yd += dppf<0x4E>(yd);
;                     sa += dppf<0x141>(sa); yd += dppf<0x141>(yd);
;                     sa += dppf<0x140>(sa); yd += dppf<0x140>(yd);
;                     if (q > 0) { if (q <= 16) ykA = (j == q - 1) ? yd : ykA; else ykB = (j == q - 17) ? yd : ykB; }
;                     const f32x2 u01 = S01 * (f32x2){wv.x, wv.y} + (f32x2){kv.x, kv.y} * vv, u23 = S23 * (f32x2){wv.z, wv.w} + (f32x2){kv.z, kv.w} * vv;
;                     S01 = u01 + (f32x2){bv.x, bv.y} * sa; S23 = u23 + (f32x2){bv.z, bv.w} * sa;
;                     f32x2 y2 = S01 * (f32x2){rv.x, rv.y}; y2 = S23 * (f32x2){rv.z, rv.w} + y2;
;                     yd = y2.x + y2.y;
;                 }
	v_mul_f32_e32 v212, v58, v200
	v_mul_f32_e32 v213, v59, v201
	v_mul_f32_e32 v204, v58, v72
	v_mul_f32_e32 v205, v59, v73
	v_fmac_f32_e32 v212, v60, v202
	v_fmac_f32_e32 v213, v61, v203
	v_fmac_f32_e32 v204, v60, v74
	v_fmac_f32_e32 v205, v61, v75
	v_add_f32_e32 v212, v212, v213
	v_add_f32_e32 v204, v204, v205
	ds_read_b128 v[104:107], v195 offset:14784
	ds_read_b128 v[108:111], v195 offset:15040
	ds_read_b128 v[112:115], v195 offset:15296
	ds_read_b128 v[196:199], v195 offset:15552
	ds_read_b128 v[200:203], v195 offset:15808
	ds_read_b32 v182, v127 offset:16064
	v_mul_f32_e32 v208, v58, v64
	v_mul_f32_e32 v209, v59, v65
	v_add_f32_dpp v204, v204, v204 quad_perm:[1,0,3,2] row_mask:0xf bank_mask:0xf bound_ctrl:1
	v_add_f32_dpp v212, v212, v212 quad_perm:[1,0,3,2] row_mask:0xf bank_mask:0xf bound_ctrl:1
	v_mul_f32_e32 v210, v60, v66
	v_add_f32_dpp v204, v204, v204 quad_perm:[2,3,0,1] row_mask:0xf bank_mask:0xf bound_ctrl:1
	v_add_f32_dpp v212, v212, v212 quad_perm:[2,3,0,1] row_mask:0xf bank_mask:0xf bound_ctrl:1
	v_mul_f32_e32 v211, v61, v67
	v_add_f32_dpp v204, v204, v204 row_half_mirror row_mask:0xf bank_mask:0xf bound_ctrl:1
	v_add_f32_dpp v212, v212, v212 row_half_mirror row_mask:0xf bank_mask:0xf bound_ctrl:1
	v_fmac_f32_e32 v208, v68, v62
	v_add_f32_dpp v204, v204, v204 row_mirror row_mask:0xf bank_mask:0xf bound_ctrl:1
	v_add_f32_dpp v212, v212, v212 row_mirror row_mask:0xf bank_mask:0xf bound_ctrl:1
	v_fmac_f32_e32 v209, v69, v62
	v_fmac_f32_e32 v210, v70, v62
	v_fmac_f32_e32 v211, v71, v62
	v_cndmask_b32_e64 v214, v214, v212, s[64:65]
	v_fma_f32 v58, v76, v204, v208
	v_fma_f32 v59, v77, v204, v209
	v_fma_f32 v60, v78, v204, v210
	v_fma_f32 v61, v79, v204, v211
	s_waitcnt lgkmcnt(6)
	v_mul_f32_e32 v212, v58, v80
	v_mul_f32_e32 v213, v59, v81
	v_mul_f32_e32 v204, v58, v92
	v_mul_f32_e32 v205, v59, v93
	v_fmac_f32_e32 v212, v60, v82
	v_fmac_f32_e32 v213, v61, v83
	v_fmac_f32_e32 v204, v60, v94
	v_fmac_f32_e32 v205, v61, v95
	v_add_f32_e32 v212, v212, v213
	v_add_f32_e32 v204, v204, v205
	ds_read_b128 v[64:67], v195 offset:16128
	ds_read_b128 v[68:71], v195 offset:16384
	ds_read_b128 v[72:75], v195 offset:16640
	ds_read_b128 v[76:79], v195 offset:16896
	ds_read_b128 v[80:83], v195 offset:17152
	ds_read_b32 v62, v127 offset:17408
	v_mul_f32_e32 v208, v58, v84
	v_mul_f32_e32 v209, v59, v85
	v_add_f32_dpp v204, v204, v204 quad_perm:[1,0,3,2] row_mask:0xf bank_mask:0xf bound_ctrl:1
	v_add_f32_dpp v212, v212, v212 quad_perm:[1,0,3,2] row_mask:0xf bank_mask:0xf bound_ctrl:1
	v_mul_f32_e32 v210, v60, v86
	v_add_f32_dpp v204, v204, v204 quad_perm:[2,3,0,1] row_mask:0xf bank_mask:0xf bound_ctrl:1
	v_add_f32_dpp v212, v212, v212 quad_perm:[2,3,0,1] row_mask:0xf bank_mask:0xf bound_ctrl:1
	v_mul_f32_e32 v211, v61, v87
	v_add_f32_dpp v204, v204, v204 row_half_mirror row_mask:0xf bank_mask:0xf bound_ctrl:1
	v_add_f32_dpp v212, v212, v212 row_half_mirror row_mask:0xf bank_mask:0xf bound_ctrl:1
	v_fmac_f32_e32 v208, v88, v63
	v_add_f32_dpp v204, v204, v204 row_mirror row_mask:0xf bank_mask:0xf bound_ctrl:1
	v_add_f32_dpp v212, v212, v212 row_mirror row_mask:0xf bank_mask:0xf bound_ctrl:1
	v_fmac_f32_e32 v209, v89, v63
	v_fmac_f32_e32 v210, v90, v63
	v_fmac_f32_e32 v211, v91, v63
	v_cndmask_b32_e64 v214, v214, v212, s[66:67]
	v_fma_f32 v58, v96, v204, v208
	v_fma_f32 v59, v97, v204, v209
	v_fma_f32 v60, v98, v204, v210
	v_fma_f32 v61, v99, v204, v211
	s_waitcnt lgkmcnt(6)
	v_mul_f32_e32 v212, v58, v100
	v_mul_f32_e32 v213, v59, v101
	v_mul_f32_e32 v204, v58, v112
	v_mul_f32_e32 v205, v59, v113
	v_fmac_f32_e32 v212, v60, v102
	v_fmac_f32_e32 v213, v61, v103
	v_fmac_f32_e32 v204, v60, v114
	v_fmac_f32_e32 v205, v61, v115
	v_add_f32_e32 v212, v212, v213
	v_add_f32_e32 v204, v204, v205
	ds_read_b128 v[84:87], v195 offset:17472
	ds_read_b128 v[88:91], v195 offset:17728
	ds_read_b128 v[92:95], v195 offset:17984
	ds_read_b128 v[96:99], v195 offset:18240
	ds_read_b128 v[100:103], v195 offset:18496
	ds_read_b32 v63, v127 offset:18752
	v_mul_f32_e32 v208, v58, v104
	v_mul_f32_e32 v209, v59, v105
	v_add_f32_dpp v204, v204, v204 quad_perm:[1,0,3,2] row_mask:0xf bank_mask:0xf bound_ctrl:1
	v_add_f32_dpp v212, v212, v212 quad_perm:[1,0,3,2] row_mask:0xf bank_mask:0xf bound_ctrl:1
	v_mul_f32_e32 v210, v60, v106
	v_add_f32_dpp v204, v204, v204 quad_perm:[2,3,0,1] row_mask:0xf bank_mask:0xf bound_ctrl:1
	v_add_f32_dpp v212, v212, v212 quad_perm:[2,3,0,1] row_mask:0xf bank_mask:0xf bound_ctrl:1
	v_mul_f32_e32 v211, v61, v107
	v_add_f32_dpp v204, v204, v204 row_half_mirror row_mask:0xf bank_mask:0xf bound_ctrl:1
	v_add_f32_dpp v212, v212, v212 row_half_mirror row_mask:0xf bank_mask:0xf bound_ctrl:1
	v_fmac_f32_e32 v208, v108, v182
	v_add_f32_dpp v204, v204, v204 row_mirror row_mask:0xf bank_mask:0xf bound_ctrl:1
	v_add_f32_dpp v212, v212, v212 row_mirror row_mask:0xf bank_mask:0xf bound_ctrl:1
	v_fmac_f32_e32 v209, v109, v182
	v_fmac_f32_e32 v210, v110, v182
	v_fmac_f32_e32 v211, v111, v182
	v_cndmask_b32_e64 v214, v214, v212, s[68:69]
	v_fma_f32 v58, v196, v204, v208
	v_fma_f32 v59, v197, v204, v209
	v_fma_f32 v60, v198, v204, v210
	v_fma_f32 v61, v199, v204, v211
	s_waitcnt lgkmcnt(6)
; #define LAS __attribute__((address_space(3)))
; template <int CTRL> __device__ __forceinline__ float dppf(float v) { return __int_as_float(__builtin_amdgcn_update_dpp(0, __float_as_int(v), CTRL, 0xf, 0xf, true)); }
; __device__ __forceinline__ void scan_phase(const Args& a, LAS unsigned char* lds, const bf16* Z, const float* W, const bf16* Aa, const bf16* KK, float* Y, int tid, int lane, int wave) {
;     ...
;                 for (int q = 0; q < SCH; ++q) {
;                     const f32x4 wv = pw[q % 3], kv = pk[q % 3], av = pa[q % 3], bv = pb[q % 3], rv = pr[q % 3]; const float vv = pv[q % 3];
;                     if (q + 2 < SCH) {
;                         const LAS float* p = sb + (q + 2) * SROW; const int i = (q + 2) % 3;
;                         pw[i] = *(const LAS f32x4*)p; pk[i] = *(const LAS f32x4*)(p + 64); pa[i] = *(const LAS f32x4*)(p + 128); pb[i] = *(const LAS f32x4*)(p + 192); pr[i] = *(const LAS f32x4*)(p + 256);
;                         pv[i] = vb[(q + 2) * SROW];
;                     }
;                     f32x2 t2 = S01 * (f32x2){av.x, av.y}; t2 = S23 * (f32x2){av.z, av.w} + t2;
;                     float sa = t2.x + t2.y;
;                     sa += dppf<0xB1>(sa); yd += dppf<0xB1>(yd);
;                     sa += dppf<0x4E>(sa); yd += dppf<0x4E>(yd);
;                     sa += dppf<0x141>(sa); yd += dppf<0x141>(yd);
;                     sa += dppf<0x140>(sa); yd += dppf<0x140>(yd);
;                     if (q > 0) { if (q <= 16) ykA = (j == q - 1) ? yd : ykA; else ykB = (j == q - 17) ? yd : ykB; }
;                     const f32x2 u01 = S01 * (f32x2){wv.x, wv.y} + (f32x2){kv.x, kv.y} * vv, u23 = S23 * (f32x2){wv.z, wv.w} + (f32x2){kv.z, kv.w} * vv;
;                     S01 = u01 + (f32x2){bv.x, bv.y} * sa; S23 = u23 + (f32x2){bv.z, bv.w} * sa;
;                     f32x2 y2 = S01 * (f32x2){rv.x, rv.y}; y2 = S23 * (f32x2){rv.z, rv.w} + y2;
;                     yd = y2.x + y2.y;
;                 }
	v_mul_f32_e32 v212, v58, v200
	v_mul_f32_e32 v213, v59, v201
	v_mul_f32_e32 v204, v58, v72
	v_mul_f32_e32 v205, v59, v73
	v_fmac_f32_e32 v212, v60, v202
	v_fmac_f32_e32 v213, v61, v203
	v_fmac_f32_e32 v204, v60, v74
	v_fmac_f32_e32 v205, v61, v75
	v_add_f32_e32 v212, v212, v213
	v_add_f32_e32 v204, v204, v205
	ds_read_b128 v[104:107], v195 offset:18816
	ds_read_b128 v[108:111], v195 offset:19072
	ds_read_b128 v[112:115], v195 offset:19328
	ds_read_b128 v[196:199], v195 offset:19584
	ds_read_b128 v[200:203], v195 offset:19840
	ds_read_b32 v182, v127 offset:20096
	v_mul_f32_e32 v208, v58, v64
	v_mul_f32_e32 v209, v59, v65
	v_add_f32_dpp v204, v204, v204 quad_perm:[1,0,3,2] row_mask:0xf bank_mask:0xf bound_ctrl:1
	v_add_f32_dpp v212, v212, v212 quad_perm:[1,0,3,2] row_mask:0xf bank_mask:0xf bound_ctrl:1
	v_mul_f32_e32 v210, v60, v66
	v_add_f32_dpp v204, v204, v204 quad_perm:[2,3,0,1] row_mask:0xf bank_mask:0xf bound_ctrl:1
	v_add_f32_dpp v212, v212, v212 quad_perm:[2,3,0,1] row_mask:0xf bank_mask:0xf bound_ctrl:1
	v_mul_f32_e32 v211, v61, v67
	v_add_f32_dpp v204, v204, v204 row_half_mirror row_mask:0xf bank_mask:0xf bound_ctrl:1
	v_add_f32_dpp v212, v212, v212 row_half_mirror row_mask:0xf bank_mask:0xf bound_ctrl:1
	v_fmac_f32_e32 v208, v68, v62
	v_add_f32_dpp v204, v204, v204 row_mirror row_mask:0xf bank_mask:0xf bound_ctrl:1
	v_add_f32_dpp v212, v212, v212 row_mirror row_mask:0xf bank_mask:0xf bound_ctrl:1
	v_fmac_f32_e32 v209, v69, v62
	v_fmac_f32_e32 v210, v70, v62
	v_fmac_f32_e32 v211, v71, v62
	v_cndmask_b32_e64 v214, v214, v212, s[70:71]
	v_fma_f32 v58, v76, v204, v208
	v_fma_f32 v59, v77, v204, v209
	v_fma_f32 v60, v78, v204, v210
	v_fma_f32 v61, v79, v204, v211
	s_waitcnt lgkmcnt(6)
	v_mul_f32_e32 v212, v58, v80
	v_mul_f32_e32 v213, v59, v81
	v_mul_f32_e32 v204, v58, v92
	v_mul_f32_e32 v205, v59, v93
	v_fmac_f32_e32 v212, v60, v82
	v_fmac_f32_e32 v213, v61, v83
	v_fmac_f32_e32 v204, v60, v94
	v_fmac_f32_e32 v205, v61, v95
	v_add_f32_e32 v212, v212, v213
	v_add_f32_e32 v204, v204, v205
	ds_read_b128 v[64:67], v195 offset:20160
	ds_read_b128 v[68:71], v195 offset:20416
	ds_read_b128 v[72:75], v195 offset:20672
	ds_read_b128 v[76:79], v195 offset:20928
	ds_read_b128 v[80:83], v195 offset:21184
	ds_read_b32 v62, v127 offset:21440
	v_mul_f32_e32 v208, v58, v84
	v_mul_f32_e32 v209, v59, v85
	v_add_f32_dpp v204, v204, v204 quad_perm:[1,0,3,2] row_mask:0xf bank_mask:0xf bound_ctrl:1
	v_add_f32_dpp v212, v212, v212 quad_perm:[1,0,3,2] row_mask:0xf bank_mask:0xf bound_ctrl:1
	v_mul_f32_e32 v210, v60, v86
	v_add_f32_dpp v204, v204, v204 quad_perm:[2,3,0,1] row_mask:0xf bank_mask:0xf bound_ctrl:1
	v_add_f32_dpp v212, v212, v212 quad_perm:[2,3,0,1] row_mask:0xf bank_mask:0xf bound_ctrl:1
	v_mul_f32_e32 v211, v61, v87
	v_add_f32_dpp v204, v204, v204 row_half_mirror row_mask:0xf bank_mask:0xf bound_ctrl:1
	v_add_f32_dpp v212, v212, v212 row_half_mirror row_mask:0xf bank_mask:0xf bound_ctrl:1
	v_fmac_f32_e32 v208, v88, v63
	v_add_f32_dpp v204, v204, v204 row_mirror row_mask:0xf bank_mask:0xf bound_ctrl:1
	v_add_f32_dpp v212, v212, v212 row_mirror row_mask:0xf bank_mask:0xf bound_ctrl:1
	v_fmac_f32_e32 v209, v89, v63
	v_fmac_f32_e32 v210, v90, v63
	v_fmac_f32_e32 v211, v91, v63
	v_cndmask_b32_e64 v214, v214, v212, s[72:73]
	v_fma_f32 v58, v96, v204, v208
	v_fma_f32 v59, v97, v204, v209
	v_fma_f32 v60, v98, v204, v210
	v_fma_f32 v61, v99, v204, v211
	s_waitcnt lgkmcnt(6)
	v_mul_f32_e32 v212, v58, v100
	v_mul_f32_e32 v213, v59, v101
	v_mul_f32_e32 v204, v58, v112
	v_mul_f32_e32 v205, v59, v113
	v_fmac_f32_e32 v212, v60, v102
	v_fmac_f32_e32 v213, v61, v103
	v_fmac_f32_e32 v204, v60, v114
	v_fmac_f32_e32 v205, v61, v115
	v_add_f32_e32 v212, v212, v213
	v_add_f32_e32 v204, v204, v205
	ds_read_b128 v[84:87], v195 offset:21504
	ds_read_b128 v[88:91], v195 offset:21760
	ds_read_b128 v[92:95], v195 offset:22016
	ds_read_b128 v[96:99], v195 offset:22272
	ds_read_b128 v[100:103], v195 offset:22528
	ds_read_b32 v63, v127 offset:22784
	v_mul_f32_e32 v208, v58, v104
	v_mul_f32_e32 v209, v59, v105
	v_add_f32_dpp v204, v204, v204 quad_perm:[1,0,3,2] row_mask:0xf bank_mask:0xf bound_ctrl:1
	v_add_f32_dpp v212, v212, v212 quad_perm:[1,0,3,2] row_mask:0xf bank_mask:0xf bound_ctrl:1
	v_mul_f32_e32 v210, v60, v106
	v_add_f32_dpp v204, v204, v204 quad_perm:[2,3,0,1] row_mask:0xf bank_mask:0xf bound_ctrl:1
	v_add_f32_dpp v212, v212, v212 quad_perm:[2,3,0,1] row_mask:0xf bank_mask:0xf bound_ctrl:1
	v_mul_f32_e32 v211, v61, v107
	v_add_f32_dpp v204, v204, v204 row_half_mirror row_mask:0xf bank_mask:0xf bound_ctrl:1
	v_add_f32_dpp v212, v212, v212 row_half_mirror row_mask:0xf bank_mask:0xf bound_ctrl:1
	v_fmac_f32_e32 v208, v108, v182
	v_add_f32_dpp v204, v204, v204 row_mirror row_mask:0xf bank_mask:0xf bound_ctrl:1
	v_add_f32_dpp v212, v212, v212 row_mirror row_mask:0xf bank_mask:0xf bound_ctrl:1
	v_fmac_f32_e32 v209, v109, v182
	v_fmac_f32_e32 v210, v110, v182
	v_fmac_f32_e32 v211, v111, v182
	v_cndmask_b32_e64 v214, v214, v212, s[74:75]
	v_fma_f32 v58, v196, v204, v208
	v_fma_f32 v59, v197, v204, v209
	v_fma_f32 v60, v198, v204, v210
	v_fma_f32 v61, v199, v204, v211
	s_waitcnt lgkmcnt(6)
; #define LAS __attribute__((address_space(3)))
; template <int CTRL> __device__ __forceinline__ float dppf(float v) { return __int_as_float(__builtin_amdgcn_update_dpp(0, __float_as_int(v), CTRL, 0xf, 0xf, true)); }
; __device__ __forceinline__ void scan_phase(const Args& a, LAS unsigned char* lds, const bf16* Z, const float* W, const bf16* Aa, const bf16* KK, float* Y, int tid, int lane, int wave) {
;     ...
;                 for (int q = 0; q < SCH; ++q) {
;                     const f32x4 wv = pw[q % 3], kv = pk[q % 3], av = pa[q % 3], bv = pb[q % 3], rv = pr[q % 3]; const float vv = pv[q % 3];
;                     if (q + 2 < SCH) {
;                         const LAS float* p = sb + (q + 2) * SROW; const int i = (q + 2) % 3;
;                         pw[i] = *(const LAS f32x4*)p; pk[i] = *(const LAS f32x4*)(p + 64); pa[i] = *(const LAS f32x4*)(p + 128); pb[i] = *(const LAS f32x4*)(p + 192); pr[i] = *(const LAS f32x4*)(p + 256);
;                         pv[i] = vb[(q + 2) * SROW];
;                     }
;                     f32x2 t2 = S01 * (f32x2){av.x, av.y}; t2 = S23 * (f32x2){av.z, av.w} + t2;
;                     float sa = t2.x + t2.y;
;                     sa += dppf<0xB1>(sa); yd += dppf<0xB1>(yd);
;                     sa += dppf<0x4E>(sa); yd += dppf<0x4E>(yd);
;                     sa += dppf<0x141>(sa); yd += dppf<0x141>(yd);
;                     sa += dppf<0x140>(sa); yd += dppf<0x140>(yd);
;                     if (q > 0) { if (q <= 16) ykA = (j == q - 1) ? yd : ykA; else ykB = (j == q - 17) ? yd : ykB; }
;                     const f32x2 u01 = S01 * (f32x2){wv.x, wv.y} + (f32x2){kv.x, kv.y} * vv, u23 = S23 * (f32x2){wv.z, wv.w} + (f32x2){kv.z, kv.w} * vv;
;                     S01 = u01 + (f32x2){bv.x, bv.y} * sa; S23 = u23 + (f32x2){bv.z, bv.w} * sa;
;                     f32x2 y2 = S01 * (f32x2){rv.x, rv.y}; y2 = S23 * (f32x2){rv.z, rv.w} + y2;
;                     yd = y2.x + y2.y;
;                 }
	v_mul_f32_e32 v212, v58, v200
	v_mul_f32_e32 v213, v59, v201
	v_mul_f32_e32 v204, v58, v72
	v_mul_f32_e32 v205, v59, v73
	v_fmac_f32_e32 v212, v60, v202
	v_fmac_f32_e32 v213, v61, v203
	v_fmac_f32_e32 v204, v60, v74
	v_fmac_f32_e32 v205, v61, v75
	v_add_f32_e32 v212, v212, v213
	v_add_f32_e32 v204, v204, v205
	ds_read_b128 v[104:107], v195 offset:22848
	ds_read_b128 v[108:111], v195 offset:23104
	ds_read_b128 v[112:115], v195 offset:23360
	ds_read_b128 v[196:199], v195 offset:23616
	ds_read_b128 v[200:203], v195 offset:23872
	ds_read_b32 v182, v127 offset:24128
	v_mul_f32_e32 v208, v58, v64
	v_mul_f32_e32 v209, v59, v65
	v_add_f32_dpp v204, v204, v204 quad_perm:[1,0,3,2] row_mask:0xf bank_mask:0xf bound_ctrl:1
	v_add_f32_dpp v212, v212, v212 quad_perm:[1,0,3,2] row_mask:0xf bank_mask:0xf bound_ctrl:1
	v_mul_f32_e32 v210, v60, v66
	v_add_f32_dpp v204, v204, v204 quad_perm:[2,3,0,1] row_mask:0xf bank_mask:0xf bound_ctrl:1
	v_add_f32_dpp v212, v212, v212 quad_perm:[2,3,0,1] row_mask:0xf bank_mask:0xf bound_ctrl:1
	v_mul_f32_e32 v211, v61, v67
	v_add_f32_dpp v204, v204, v204 row_half_mirror row_mask:0xf bank_mask:0xf bound_ctrl:1
	v_add_f32_dpp v212, v212, v212 row_half_mirror row_mask:0xf bank_mask:0xf bound_ctrl:1
	v_fmac_f32_e32 v208, v68, v62
	v_add_f32_dpp v204, v204, v204 row_mirror row_mask:0xf bank_mask:0xf bound_ctrl:1
	v_add_f32_dpp v212, v212, v212 row_mirror row_mask:0xf bank_mask:0xf bound_ctrl:1
	v_fmac_f32_e32 v209, v69, v62
	v_fmac_f32_e32 v210, v70, v62
	v_fmac_f32_e32 v211, v71, v62
	v_cndmask_b32_e64 v214, v214, v212, s[76:77]
	v_fma_f32 v58, v76, v204, v208
	v_fma_f32 v59, v77, v204, v209
	v_fma_f32 v60, v78, v204, v210
	v_fma_f32 v61, v79, v204, v211
	s_waitcnt lgkmcnt(6)
	v_mul_f32_e32 v212, v58, v80
	v_mul_f32_e32 v213, v59, v81
	v_mul_f32_e32 v204, v58, v92
	v_mul_f32_e32 v205, v59, v93
	v_fmac_f32_e32 v212, v60, v82
	v_fmac_f32_e32 v213, v61, v83
	v_fmac_f32_e32 v204, v60, v94
	v_fmac_f32_e32 v205, v61, v95
	v_add_f32_e32 v212, v212, v213
	v_add_f32_e32 v204, v204, v205
	ds_read_b128 v[64:67], v195 offset:24192
	ds_read_b128 v[68:71], v195 offset:24448
	ds_read_b128 v[72:75], v195 offset:24704
	ds_read_b128 v[76:79], v195 offset:24960
	ds_read_b128 v[80:83], v195 offset:25216
	ds_read_b32 v62, v127 offset:25472
	v_mul_f32_e32 v208, v58, v84
	v_mul_f32_e32 v209, v59, v85
	v_add_f32_dpp v204, v204, v204 quad_perm:[1,0,3,2] row_mask:0xf bank_mask:0xf bound_ctrl:1
	v_add_f32_dpp v212, v212, v212 quad_perm:[1,0,3,2] row_mask:0xf bank_mask:0xf bound_ctrl:1
	v_mul_f32_e32 v210, v60, v86
	v_add_f32_dpp v204, v204, v204 quad_perm:[2,3,0,1] row_mask:0xf bank_mask:0xf bound_ctrl:1
	v_add_f32_dpp v212, v212, v212 quad_perm:[2,3,0,1] row_mask:0xf bank_mask:0xf bound_ctrl:1
	v_mul_f32_e32 v211, v61, v87
	v_add_f32_dpp v204, v204, v204 row_half_mirror row_mask:0xf bank_mask:0xf bound_ctrl:1
	v_add_f32_dpp v212, v212, v212 row_half_mirror row_mask:0xf bank_mask:0xf bound_ctrl:1
	v_fmac_f32_e32 v208, v88, v63
	v_add_f32_dpp v204, v204, v204 row_mirror row_mask:0xf bank_mask:0xf bound_ctrl:1
	v_add_f32_dpp v212, v212, v212 row_mirror row_mask:0xf bank_mask:0xf bound_ctrl:1
	v_fmac_f32_e32 v209, v89, v63
	v_fmac_f32_e32 v210, v90, v63
	v_fmac_f32_e32 v211, v91, v63
	v_cndmask_b32_e64 v214, v214, v212, s[96:97]
	v_fma_f32 v58, v96, v204, v208
	v_fma_f32 v59, v97, v204, v209
	v_fma_f32 v60, v98, v204, v210
	v_fma_f32 v61, v99, v204, v211
	s_waitcnt lgkmcnt(6)
	v_mul_f32_e32 v212, v58, v100
	v_mul_f32_e32 v213, v59, v101
	v_mul_f32_e32 v204, v58, v112
	v_mul_f32_e32 v205, v59, v113
	v_fmac_f32_e32 v212, v60, v102
	v_fmac_f32_e32 v213, v61, v103
	v_fmac_f32_e32 v204, v60, v114
	v_fmac_f32_e32 v205, v61, v115
	v_add_f32_e32 v212, v212, v213
	v_add_f32_e32 v204, v204, v205
	ds_read_b128 v[84:87], v195 offset:25536
	ds_read_b128 v[88:91], v195 offset:25792
	ds_read_b128 v[92:95], v195 offset:26048
	ds_read_b128 v[96:99], v195 offset:26304
	ds_read_b128 v[100:103], v195 offset:26560
	ds_read_b32 v63, v127 offset:26816
	v_mul_f32_e32 v208, v58, v104
	v_mul_f32_e32 v209, v59, v105
	v_add_f32_dpp v204, v204, v204 quad_perm:[1,0,3,2] row_mask:0xf bank_mask:0xf bound_ctrl:1
	v_add_f32_dpp v212, v212, v212 quad_perm:[1,0,3,2] row_mask:0xf bank_mask:0xf bound_ctrl:1
	v_mul_f32_e32 v210, v60, v106
	v_add_f32_dpp v204, v204, v204 quad_perm:[2,3,0,1] row_mask:0xf bank_mask:0xf bound_ctrl:1
	v_add_f32_dpp v212, v212, v212 quad_perm:[2,3,0,1] row_mask:0xf bank_mask:0xf bound_ctrl:1
	v_mul_f32_e32 v211, v61, v107
	v_add_f32_dpp v204, v204, v204 row_half_mirror row_mask:0xf bank_mask:0xf bound_ctrl:1
	v_add_f32_dpp v212, v212, v212 row_half_mirror row_mask:0xf bank_mask:0xf bound_ctrl:1
	v_fmac_f32_e32 v208, v108, v182
	v_add_f32_dpp v204, v204, v204 row_mirror row_mask:0xf bank_mask:0xf bound_ctrl:1
	v_add_f32_dpp v212, v212, v212 row_mirror row_mask:0xf bank_mask:0xf bound_ctrl:1
	v_fmac_f32_e32 v209, v109, v182
	v_fmac_f32_e32 v210, v110, v182
	v_fmac_f32_e32 v211, v111, v182
	v_cndmask_b32_e64 v215, 0, v212, s[82:83]
	v_fma_f32 v58, v196, v204, v208
	v_fma_f32 v59, v197, v204, v209
	v_fma_f32 v60, v198, v204, v210
	v_fma_f32 v61, v199, v204, v211
	s_waitcnt lgkmcnt(6)
; #define LAS __attribute__((address_space(3)))
; template <int CTRL> __device__ __forceinline__ float dppf(float v) { return __int_as_float(__builtin_amdgcn_update_dpp(0, __float_as_int(v), CTRL, 0xf, 0xf, true)); }
; __device__ __forceinline__ void scan_phase(const Args& a, LAS unsigned char* lds, const bf16* Z, const float* W, const bf16* Aa, const bf16* KK, float* Y, int tid, int lane, int wave) {
;     ...
;                 for (int q = 0; q < SCH; ++q) {
;                     const f32x4 wv = pw[q % 3], kv = pk[q % 3], av = pa[q % 3], bv = pb[q % 3], rv = pr[q % 3]; const float vv = pv[q % 3];
;                     if (q + 2 < SCH) {
;                         const LAS float* p = sb + (q + 2) * SROW; const int i = (q + 2) % 3;
;                         pw[i] = *(const LAS f32x4*)p; pk[i] = *(const LAS f32x4*)(p + 64); pa[i] = *(const LAS f32x4*)(p + 128); pb[i] = *(const LAS f32x4*)(p + 192); pr[i] = *(const LAS f32x4*)(p + 256);
;                         pv[i] = vb[(q + 2) * SROW];
;                     }
;                     f32x2 t2 = S01 * (f32x2){av.x, av.y}; t2 = S23 * (f32x2){av.z, av.w} + t2;
;                     float sa = t2.x + t2.y;
;                     sa += dppf<0xB1>(sa); yd += dppf<0xB1>(yd);
;                     sa += dppf<0x4E>(sa); yd += dppf<0x4E>(yd);
;                     sa += dppf<0x141>(sa); yd += dppf<0x141>(yd);
;                     sa += dppf<0x140>(sa); yd += dppf<0x140>(yd);
;                     if (q > 0) { if (q <= 16) ykA = (j == q - 1) ? yd : ykA; else ykB = (j == q - 17) ? yd : ykB; }
;                     const f32x2 u01 = S01 * (f32x2){wv.x, wv.y} + (f32x2){kv.x, kv.y} * vv, u23 = S23 * (f32x2){wv.z, wv.w} + (f32x2){kv.z, kv.w} * vv;
;                     S01 = u01 + (f32x2){bv.x, bv.y} * sa; S23 = u23 + (f32x2){bv.z, bv.w} * sa;
;                     f32x2 y2 = S01 * (f32x2){rv.x, rv.y}; y2 = S23 * (f32x2){rv.z, rv.w} + y2;
;                     yd = y2.x + y2.y;
;                 }
	v_mul_f32_e32 v212, v58, v200
	v_mul_f32_e32 v213, v59, v201
	v_mul_f32_e32 v204, v58, v72
	v_mul_f32_e32 v205, v59, v73
	v_fmac_f32_e32 v212, v60, v202
	v_fmac_f32_e32 v213, v61, v203
	v_fmac_f32_e32 v204, v60, v74
	v_fmac_f32_e32 v205, v61, v75
	v_add_f32_e32 v212, v212, v213
	v_add_f32_e32 v204, v204, v205
	ds_read_b128 v[104:107], v195 offset:26880
	ds_read_b128 v[108:111], v195 offset:27136
	ds_read_b128 v[112:115], v195 offset:27392
	ds_read_b128 v[196:199], v195 offset:27648
	ds_read_b128 v[200:203], v195 offset:27904
	ds_read_b32 v182, v127 offset:28160
	v_mul_f32_e32 v208, v58, v64
	v_mul_f32_e32 v209, v59, v65
	v_add_f32_dpp v204, v204, v204 quad_perm:[1,0,3,2] row_mask:0xf bank_mask:0xf bound_ctrl:1
	v_add_f32_dpp v212, v212, v212 quad_perm:[1,0,3,2] row_mask:0xf bank_mask:0xf bound_ctrl:1
	v_mul_f32_e32 v210, v60, v66
	v_add_f32_dpp v204, v204, v204 quad_perm:[2,3,0,1] row_mask:0xf bank_mask:0xf bound_ctrl:1
	v_add_f32_dpp v212, v212, v212 quad_perm:[2,3,0,1] row_mask:0xf bank_mask:0xf bound_ctrl:1
	v_mul_f32_e32 v211, v61, v67
	v_add_f32_dpp v204, v204, v204 row_half_mirror row_mask:0xf bank_mask:0xf bound_ctrl:1
	v_add_f32_dpp v212, v212, v212 row_half_mirror row_mask:0xf bank_mask:0xf bound_ctrl:1
	v_fmac_f32_e32 v208, v68, v62
	v_add_f32_dpp v204, v204, v204 row_mirror row_mask:0xf bank_mask:0xf bound_ctrl:1
	v_add_f32_dpp v212, v212, v212 row_mirror row_mask:0xf bank_mask:0xf bound_ctrl:1
	v_fmac_f32_e32 v209, v69, v62
	v_fmac_f32_e32 v210, v70, v62
	v_fmac_f32_e32 v211, v71, v62
	v_cndmask_b32_e64 v215, v215, v212, s[80:81]
	v_fma_f32 v58, v76, v204, v208
	v_fma_f32 v59, v77, v204, v209
	v_fma_f32 v60, v78, v204, v210
	v_fma_f32 v61, v79, v204, v211
	s_waitcnt lgkmcnt(6)
	v_mul_f32_e32 v212, v58, v80
	v_mul_f32_e32 v213, v59, v81
	v_mul_f32_e32 v204, v58, v92
	v_mul_f32_e32 v205, v59, v93
	v_fmac_f32_e32 v212, v60, v82
	v_fmac_f32_e32 v213, v61, v83
	v_fmac_f32_e32 v204, v60, v94
	v_fmac_f32_e32 v205, v61, v95
	v_add_f32_e32 v212, v212, v213
	v_add_f32_e32 v204, v204, v205
	ds_read_b128 v[64:67], v195 offset:28224
	ds_read_b128 v[68:71], v195 offset:28480
	ds_read_b128 v[72:75], v195 offset:28736
	ds_read_b128 v[76:79], v195 offset:28992
	ds_read_b128 v[80:83], v195 offset:29248
	ds_read_b32 v62, v127 offset:29504
	v_mul_f32_e32 v208, v58, v84
	v_mul_f32_e32 v209, v59, v85
	v_add_f32_dpp v204, v204, v204 quad_perm:[1,0,3,2] row_mask:0xf bank_mask:0xf bound_ctrl:1
	v_add_f32_dpp v212, v212, v212 quad_perm:[1,0,3,2] row_mask:0xf bank_mask:0xf bound_ctrl:1
	v_mul_f32_e32 v210, v60, v86
	v_add_f32_dpp v204, v204, v204 quad_perm:[2,3,0,1] row_mask:0xf bank_mask:0xf bound_ctrl:1
	v_add_f32_dpp v212, v212, v212 quad_perm:[2,3,0,1] row_mask:0xf bank_mask:0xf bound_ctrl:1
	v_mul_f32_e32 v211, v61, v87
	v_add_f32_dpp v204, v204, v204 row_half_mirror row_mask:0xf bank_mask:0xf bound_ctrl:1
	v_add_f32_dpp v212, v212, v212 row_half_mirror row_mask:0xf bank_mask:0xf bound_ctrl:1
	v_fmac_f32_e32 v208, v88, v63
	v_add_f32_dpp v204, v204, v204 row_mirror row_mask:0xf bank_mask:0xf bound_ctrl:1
	v_add_f32_dpp v212, v212, v212 row_mirror row_mask:0xf bank_mask:0xf bound_ctrl:1
	v_fmac_f32_e32 v209, v89, v63
	v_fmac_f32_e32 v210, v90, v63
	v_fmac_f32_e32 v211, v91, v63
	v_cndmask_b32_e64 v215, v215, v212, s[6:7]
	v_fma_f32 v58, v96, v204, v208
	v_fma_f32 v59, v97, v204, v209
	v_fma_f32 v60, v98, v204, v210
	v_fma_f32 v61, v99, v204, v211
	s_waitcnt lgkmcnt(6)
	v_mul_f32_e32 v212, v58, v100
	v_mul_f32_e32 v213, v59, v101
	v_mul_f32_e32 v204, v58, v112
	v_mul_f32_e32 v205, v59, v113
	v_fmac_f32_e32 v212, v60, v102
	v_fmac_f32_e32 v213, v61, v103
	v_fmac_f32_e32 v204, v60, v114
	v_fmac_f32_e32 v205, v61, v115
	v_add_f32_e32 v212, v212, v213
	v_add_f32_e32 v204, v204, v205
	ds_read_b128 v[84:87], v195 offset:29568
	ds_read_b128 v[88:91], v195 offset:29824
	ds_read_b128 v[92:95], v195 offset:30080
	ds_read_b128 v[96:99], v195 offset:30336
	ds_read_b128 v[100:103], v195 offset:30592
	ds_read_b32 v63, v127 offset:30848
	v_mul_f32_e32 v208, v58, v104
	v_mul_f32_e32 v209, v59, v105
	v_add_f32_dpp v204, v204, v204 quad_perm:[1,0,3,2] row_mask:0xf bank_mask:0xf bound_ctrl:1
	v_add_f32_dpp v212, v212, v212 quad_perm:[1,0,3,2] row_mask:0xf bank_mask:0xf bound_ctrl:1
	v_mul_f32_e32 v210, v60, v106
	v_add_f32_dpp v204, v204, v204 quad_perm:[2,3,0,1] row_mask:0xf bank_mask:0xf bound_ctrl:1
	v_add_f32_dpp v212, v212, v212 quad_perm:[2,3,0,1] row_mask:0xf bank_mask:0xf bound_ctrl:1
	v_mul_f32_e32 v211, v61, v107
	v_add_f32_dpp v204, v204, v204 row_half_mirror row_mask:0xf bank_mask:0xf bound_ctrl:1
	v_add_f32_dpp v212, v212, v212 row_half_mirror row_mask:0xf bank_mask:0xf bound_ctrl:1
	v_fmac_f32_e32 v208, v108, v182
	v_add_f32_dpp v204, v204, v204 row_mirror row_mask:0xf bank_mask:0xf bound_ctrl:1
	v_add_f32_dpp v212, v212, v212 row_mirror row_mask:0xf bank_mask:0xf bound_ctrl:1
	v_fmac_f32_e32 v209, v109, v182
	v_fmac_f32_e32 v210, v110, v182
	v_fmac_f32_e32 v211, v111, v182
	v_cndmask_b32_e64 v215, v215, v212, s[8:9]
	v_fma_f32 v58, v196, v204, v208
	v_fma_f32 v59, v197, v204, v209
	v_fma_f32 v60, v198, v204, v210
	v_fma_f32 v61, v199, v204, v211
	s_waitcnt lgkmcnt(6)
; #define LAS __attribute__((address_space(3)))
; template <int CTRL> __device__ __forceinline__ float dppf(float v) { return __int_as_float(__builtin_amdgcn_update_dpp(0, __float_as_int(v), CTRL, 0xf, 0xf, true)); }
; __device__ __forceinline__ void scan_phase(const Args& a, LAS unsigned char* lds, const bf16* Z, const float* W, const bf16* Aa, const bf16* KK, float* Y, int tid, int lane, int wave) {
;     ...
;                 for (int q = 0; q < SCH; ++q) {
;                     const f32x4 wv = pw[q % 3], kv = pk[q % 3], av = pa[q % 3], bv = pb[q % 3], rv = pr[q % 3]; const float vv = pv[q % 3];
;                     if (q + 2 < SCH) {
;                         const LAS float* p = sb + (q + 2) * SROW; const int i = (q + 2) % 3;
;                         pw[i] = *(const LAS f32x4*)p; pk[i] = *(const LAS f32x4*)(p + 64); pa[i] = *(const LAS f32x4*)(p + 128); pb[i] = *(const LAS f32x4*)(p + 192); pr[i] = *(const LAS f32x4*)(p + 256);
;                         pv[i] = vb[(q + 2) * SROW];
;                     }
;                     f32x2 t2 = S01 * (f32x2){av.x, av.y}; t2 = S23 * (f32x2){av.z, av.w} + t2;
;                     float sa = t2.x + t2.y;
;                     sa += dppf<0xB1>(sa); yd += dppf<0xB1>(yd);
;                     sa += dppf<0x4E>(sa); yd += dppf<0x4E>(yd);
;                     sa += dppf<0x141>(sa); yd += dppf<0x141>(yd);
;                     sa += dppf<0x140>(sa); yd += dppf<0x140>(yd);
;                     if (q > 0) { if (q <= 16) ykA = (j == q - 1) ? yd : ykA; else ykB = (j == q - 17) ? yd : ykB; }
;                     const f32x2 u01 = S01 * (f32x2){wv.x, wv.y} + (f32x2){kv.x, kv.y} * vv, u23 = S23 * (f32x2){wv.z, wv.w} + (f32x2){kv.z, kv.w} * vv;
;                     S01 = u01 + (f32x2){bv.x, bv.y} * sa; S23 = u23 + (f32x2){bv.z, bv.w} * sa;
;                     f32x2 y2 = S01 * (f32x2){rv.x, rv.y}; y2 = S23 * (f32x2){rv.z, rv.w} + y2;
;                     yd = y2.x + y2.y;
;                 }
	v_mul_f32_e32 v212, v58, v200
	v_mul_f32_e32 v213, v59, v201
	v_mul_f32_e32 v204, v58, v72
	v_mul_f32_e32 v205, v59, v73
	v_fmac_f32_e32 v212, v60, v202
	v_fmac_f32_e32 v213, v61, v203
	v_fmac_f32_e32 v204, v60, v74
	v_fmac_f32_e32 v205, v61, v75
	v_add_f32_e32 v212, v212, v213
	v_add_f32_e32 v204, v204, v205
	ds_read_b128 v[104:107], v195 offset:30912
	ds_read_b128 v[108:111], v195 offset:31168
	ds_read_b128 v[112:115], v195 offset:31424
	ds_read_b128 v[196:199], v195 offset:31680
	ds_read_b128 v[200:203], v195 offset:31936
	ds_read_b32 v182, v127 offset:32192
	v_mul_f32_e32 v208, v58, v64
	v_mul_f32_e32 v209, v59, v65
	v_add_f32_dpp v204, v204, v204 quad_perm:[1,0,3,2] row_mask:0xf bank_mask:0xf bound_ctrl:1
	v_add_f32_dpp v212, v212, v212 quad_perm:[1,0,3,2] row_mask:0xf bank_mask:0xf bound_ctrl:1
	v_mul_f32_e32 v210, v60, v66
	v_add_f32_dpp v204, v204, v204 quad_perm:[2,3,0,1] row_mask:0xf bank_mask:0xf bound_ctrl:1
	v_add_f32_dpp v212, v212, v212 quad_perm:[2,3,0,1] row_mask:0xf bank_mask:0xf bound_ctrl:1
	v_mul_f32_e32 v211, v61, v67
	v_add_f32_dpp v204, v204, v204 row_half_mirror row_mask:0xf bank_mask:0xf bound_ctrl:1
	v_add_f32_dpp v212, v212, v212 row_half_mirror row_mask:0xf bank_mask:0xf bound_ctrl:1
	v_fmac_f32_e32 v208, v68, v62
	v_add_f32_dpp v204, v204, v204 row_mirror row_mask:0xf bank_mask:0xf bound_ctrl:1
	v_add_f32_dpp v212, v212, v212 row_mirror row_mask:0xf bank_mask:0xf bound_ctrl:1
	v_fmac_f32_e32 v209, v69, v62
	v_fmac_f32_e32 v210, v70, v62
	v_fmac_f32_e32 v211, v71, v62
	v_cndmask_b32_e64 v215, v215, v212, s[10:11]
	v_fma_f32 v58, v76, v204, v208
	v_fma_f32 v59, v77, v204, v209
	v_fma_f32 v60, v78, v204, v210
	v_fma_f32 v61, v79, v204, v211
	s_waitcnt lgkmcnt(6)
	v_mul_f32_e32 v212, v58, v80
	v_mul_f32_e32 v213, v59, v81
	v_mul_f32_e32 v204, v58, v92
	v_mul_f32_e32 v205, v59, v93
	v_fmac_f32_e32 v212, v60, v82
	v_fmac_f32_e32 v213, v61, v83
	v_fmac_f32_e32 v204, v60, v94
	v_fmac_f32_e32 v205, v61, v95
	v_add_f32_e32 v212, v212, v213
	v_add_f32_e32 v204, v204, v205
	ds_read_b128 v[64:67], v195 offset:32256
	ds_read_b128 v[68:71], v195 offset:32512
	ds_read_b128 v[72:75], v195 offset:32768
	ds_read_b128 v[76:79], v195 offset:33024
	ds_read_b128 v[80:83], v195 offset:33280
	ds_read_b32 v62, v127 offset:33536
	v_mul_f32_e32 v208, v58, v84
	v_mul_f32_e32 v209, v59, v85
	v_add_f32_dpp v204, v204, v204 quad_perm:[1,0,3,2] row_mask:0xf bank_mask:0xf bound_ctrl:1
	v_add_f32_dpp v212, v212, v212 quad_perm:[1,0,3,2] row_mask:0xf bank_mask:0xf bound_ctrl:1
	v_mul_f32_e32 v210, v60, v86
	v_add_f32_dpp v204, v204, v204 quad_perm:[2,3,0,1] row_mask:0xf bank_mask:0xf bound_ctrl:1
	v_add_f32_dpp v212, v212, v212 quad_perm:[2,3,0,1] row_mask:0xf bank_mask:0xf bound_ctrl:1
	v_mul_f32_e32 v211, v61, v87
	v_add_f32_dpp v204, v204, v204 row_half_mirror row_mask:0xf bank_mask:0xf bound_ctrl:1
	v_add_f32_dpp v212, v212, v212 row_half_mirror row_mask:0xf bank_mask:0xf bound_ctrl:1
	v_fmac_f32_e32 v208, v88, v63
	v_add_f32_dpp v204, v204, v204 row_mirror row_mask:0xf bank_mask:0xf bound_ctrl:1
	v_add_f32_dpp v212, v212, v212 row_mirror row_mask:0xf bank_mask:0xf bound_ctrl:1
	v_fmac_f32_e32 v209, v89, v63
	v_fmac_f32_e32 v210, v90, v63
	v_fmac_f32_e32 v211, v91, v63
	v_cndmask_b32_e64 v215, v215, v212, s[90:91]
	v_fma_f32 v58, v96, v204, v208
	v_fma_f32 v59, v97, v204, v209
	v_fma_f32 v60, v98, v204, v210
	v_fma_f32 v61, v99, v204, v211
	s_waitcnt lgkmcnt(6)
	v_mul_f32_e32 v212, v58, v100
	v_mul_f32_e32 v213, v59, v101
	v_mul_f32_e32 v204, v58, v112
	v_mul_f32_e32 v205, v59, v113
	v_fmac_f32_e32 v212, v60, v102
	v_fmac_f32_e32 v213, v61, v103
	v_fmac_f32_e32 v204, v60, v114
	v_fmac_f32_e32 v205, v61, v115
	v_add_f32_e32 v212, v212, v213
	v_add_f32_e32 v204, v204, v205
	ds_read_b128 v[84:87], v195 offset:33600
	ds_read_b128 v[88:91], v195 offset:33856
	ds_read_b128 v[92:95], v195 offset:34112
	ds_read_b128 v[96:99], v195 offset:34368
	ds_read_b128 v[100:103], v195 offset:34624
	ds_read_b32 v63, v127 offset:34880
	v_mul_f32_e32 v208, v58, v104
	v_mul_f32_e32 v209, v59, v105
	v_add_f32_dpp v204, v204, v204 quad_perm:[1,0,3,2] row_mask:0xf bank_mask:0xf bound_ctrl:1
	v_add_f32_dpp v212, v212, v212 quad_perm:[1,0,3,2] row_mask:0xf bank_mask:0xf bound_ctrl:1
	v_mul_f32_e32 v210, v60, v106
	v_add_f32_dpp v204, v204, v204 quad_perm:[2,3,0,1] row_mask:0xf bank_mask:0xf bound_ctrl:1
	v_add_f32_dpp v212, v212, v212 quad_perm:[2,3,0,1] row_mask:0xf bank_mask:0xf bound_ctrl:1
	v_mul_f32_e32 v211, v61, v107
	v_add_f32_dpp v204, v204, v204 row_half_mirror row_mask:0xf bank_mask:0xf bound_ctrl:1
	v_add_f32_dpp v212, v212, v212 row_half_mirror row_mask:0xf bank_mask:0xf bound_ctrl:1
	v_fmac_f32_e32 v208, v108, v182
	v_add_f32_dpp v204, v204, v204 row_mirror row_mask:0xf bank_mask:0xf bound_ctrl:1
	v_add_f32_dpp v212, v212, v212 row_mirror row_mask:0xf bank_mask:0xf bound_ctrl:1
	v_fmac_f32_e32 v209, v109, v182
	v_fmac_f32_e32 v210, v110, v182
	v_fmac_f32_e32 v211, v111, v182
	v_cndmask_b32_e64 v215, v215, v212, s[60:61]
	v_fma_f32 v58, v196, v204, v208
	v_fma_f32 v59, v197, v204, v209
	v_fma_f32 v60, v198, v204, v210
	v_fma_f32 v61, v199, v204, v211
	s_waitcnt lgkmcnt(6)
; #define LAS __attribute__((address_space(3)))
; template <int CTRL> __device__ __forceinline__ float dppf(float v) { return __int_as_float(__builtin_amdgcn_update_dpp(0, __float_as_int(v), CTRL, 0xf, 0xf, true)); }
; __device__ __forceinline__ void scan_phase(const Args& a, LAS unsigned char* lds, const bf16* Z, const float* W, const bf16* Aa, const bf16* KK, float* Y, int tid, int lane, int wave) {
;     ...
;                 for (int q = 0; q < SCH; ++q) {
;                     const f32x4 wv = pw[q % 3], kv = pk[q % 3], av = pa[q % 3], bv = pb[q % 3], rv = pr[q % 3]; const float vv = pv[q % 3];
;                     if (q + 2 < SCH) {
;                         const LAS float* p = sb + (q + 2) * SROW; const int i = (q + 2) % 3;
;                         pw[i] = *(const LAS f32x4*)p; pk[i] = *(const LAS f32x4*)(p + 64); pa[i] = *(const LAS f32x4*)(p + 128); pb[i] = *(const LAS f32x4*)(p + 192); pr[i] = *(const LAS f32x4*)(p + 256);
;                         pv[i] = vb[(q + 2) * SROW];
;                     }
;                     f32x2 t2 = S01 * (f32x2){av.x, av.y}; t2 = S23 * (f32x2){av.z, av.w} + t2;
;                     float sa = t2.x + t2.y;
;                     sa += dppf<0xB1>(sa); yd += dppf<0xB1>(yd);
;                     sa += dppf<0x4E>(sa); yd += dppf<0x4E>(yd);
;                     sa += dppf<0x141>(sa); yd += dppf<0x141>(yd);
;                     sa += dppf<0x140>(sa); yd += dppf<0x140>(yd);
;                     if (q > 0) { if (q <= 16) ykA = (j == q - 1) ? yd : ykA; else ykB = (j == q - 17) ? yd : ykB; }
;                     const f32x2 u01 = S01 * (f32x2){wv.x, wv.y} + (f32x2){kv.x, kv.y} * vv, u23 = S23 * (f32x2){wv.z, wv.w} + (f32x2){kv.z, kv.w} * vv;
;                     S01 = u01 + (f32x2){bv.x, bv.y} * sa; S23 = u23 + (f32x2){bv.z, bv.w} * sa;
;                     f32x2 y2 = S01 * (f32x2){rv.x, rv.y}; y2 = S23 * (f32x2){rv.z, rv.w} + y2;
;                     yd = y2.x + y2.y;
;                 }
	v_mul_f32_e32 v212, v58, v200
	v_mul_f32_e32 v213, v59, v201
	v_mul_f32_e32 v204, v58, v72
	v_mul_f32_e32 v205, v59, v73
	v_fmac_f32_e32 v212, v60, v202
	v_fmac_f32_e32 v213, v61, v203
	v_fmac_f32_e32 v204, v60, v74
	v_fmac_f32_e32 v205, v61, v75
	v_add_f32_e32 v212, v212, v213
	v_add_f32_e32 v204, v204, v205
	ds_read_b128 v[104:107], v195 offset:34944
	ds_read_b128 v[108:111], v195 offset:35200
	ds_read_b128 v[112:115], v195 offset:35456
	ds_read_b128 v[196:199], v195 offset:35712
	ds_read_b128 v[200:203], v195 offset:35968
	ds_read_b32 v182, v127 offset:36224
	v_mul_f32_e32 v208, v58, v64
	v_mul_f32_e32 v209, v59, v65
	v_add_f32_dpp v204, v204, v204 quad_perm:[1,0,3,2] row_mask:0xf bank_mask:0xf bound_ctrl:1
	v_add_f32_dpp v212, v212, v212 quad_perm:[1,0,3,2] row_mask:0xf bank_mask:0xf bound_ctrl:1
	v_mul_f32_e32 v210, v60, v66
	v_add_f32_dpp v204, v204, v204 quad_perm:[2,3,0,1] row_mask:0xf bank_mask:0xf bound_ctrl:1
	v_add_f32_dpp v212, v212, v212 quad_perm:[2,3,0,1] row_mask:0xf bank_mask:0xf bound_ctrl:1
	v_mul_f32_e32 v211, v61, v67
	v_add_f32_dpp v204, v204, v204 row_half_mirror row_mask:0xf bank_mask:0xf bound_ctrl:1
	v_add_f32_dpp v212, v212, v212 row_half_mirror row_mask:0xf bank_mask:0xf bound_ctrl:1
	v_fmac_f32_e32 v208, v68, v62
	v_add_f32_dpp v204, v204, v204 row_mirror row_mask:0xf bank_mask:0xf bound_ctrl:1
	v_add_f32_dpp v212, v212, v212 row_mirror row_mask:0xf bank_mask:0xf bound_ctrl:1
	v_fmac_f32_e32 v209, v69, v62
	v_fmac_f32_e32 v210, v70, v62
	v_fmac_f32_e32 v211, v71, v62
	v_cndmask_b32_e64 v215, v215, v212, s[62:63]
	v_fma_f32 v58, v76, v204, v208
	v_fma_f32 v59, v77, v204, v209
	v_fma_f32 v60, v78, v204, v210
	v_fma_f32 v61, v79, v204, v211
	s_waitcnt lgkmcnt(6)
	v_mul_f32_e32 v212, v58, v80
	v_mul_f32_e32 v213, v59, v81
	v_mul_f32_e32 v204, v58, v92
	v_mul_f32_e32 v205, v59, v93
	v_fmac_f32_e32 v212, v60, v82
	v_fmac_f32_e32 v213, v61, v83
	v_fmac_f32_e32 v204, v60, v94
	v_fmac_f32_e32 v205, v61, v95
	v_add_f32_e32 v212, v212, v213
	v_add_f32_e32 v204, v204, v205
	ds_read_b128 v[64:67], v195 offset:36288
	ds_read_b128 v[68:71], v195 offset:36544
	ds_read_b128 v[72:75], v195 offset:36800
	ds_read_b128 v[76:79], v195 offset:37056
	ds_read_b128 v[80:83], v195 offset:37312
	ds_read_b32 v62, v127 offset:37568
	v_mul_f32_e32 v208, v58, v84
	v_mul_f32_e32 v209, v59, v85
	v_add_f32_dpp v204, v204, v204 quad_perm:[1,0,3,2] row_mask:0xf bank_mask:0xf bound_ctrl:1
	v_add_f32_dpp v212, v212, v212 quad_perm:[1,0,3,2] row_mask:0xf bank_mask:0xf bound_ctrl:1
	v_mul_f32_e32 v210, v60, v86
	v_add_f32_dpp v204, v204, v204 quad_perm:[2,3,0,1] row_mask:0xf bank_mask:0xf bound_ctrl:1
	v_add_f32_dpp v212, v212, v212 quad_perm:[2,3,0,1] row_mask:0xf bank_mask:0xf bound_ctrl:1
	v_mul_f32_e32 v211, v61, v87
	v_add_f32_dpp v204, v204, v204 row_half_mirror row_mask:0xf bank_mask:0xf bound_ctrl:1
	v_add_f32_dpp v212, v212, v212 row_half_mirror row_mask:0xf bank_mask:0xf bound_ctrl:1
	v_fmac_f32_e32 v208, v88, v63
	v_add_f32_dpp v204, v204, v204 row_mirror row_mask:0xf bank_mask:0xf bound_ctrl:1
	v_add_f32_dpp v212, v212, v212 row_mirror row_mask:0xf bank_mask:0xf bound_ctrl:1
	v_fmac_f32_e32 v209, v89, v63
	v_fmac_f32_e32 v210, v90, v63
	v_fmac_f32_e32 v211, v91, v63
	v_cndmask_b32_e64 v215, v215, v212, s[64:65]
	v_fma_f32 v58, v96, v204, v208
	v_fma_f32 v59, v97, v204, v209
	v_fma_f32 v60, v98, v204, v210
	v_fma_f32 v61, v99, v204, v211
	s_waitcnt lgkmcnt(6)
	v_mul_f32_e32 v212, v58, v100
	v_mul_f32_e32 v213, v59, v101
	v_mul_f32_e32 v204, v58, v112
	v_mul_f32_e32 v205, v59, v113
	v_fmac_f32_e32 v212, v60, v102
	v_fmac_f32_e32 v213, v61, v103
	v_fmac_f32_e32 v204, v60, v114
	v_fmac_f32_e32 v205, v61, v115
	v_add_f32_e32 v212, v212, v213
	v_add_f32_e32 v204, v204, v205
	ds_read_b128 v[84:87], v195 offset:37632
	ds_read_b128 v[88:91], v195 offset:37888
	ds_read_b128 v[92:95], v195 offset:38144
	ds_read_b128 v[96:99], v195 offset:38400
	ds_read_b128 v[100:103], v195 offset:38656
	ds_read_b32 v63, v127 offset:38912
	v_mul_f32_e32 v208, v58, v104
	v_mul_f32_e32 v209, v59, v105
	v_add_f32_dpp v204, v204, v204 quad_perm:[1,0,3,2] row_mask:0xf bank_mask:0xf bound_ctrl:1
	v_add_f32_dpp v212, v212, v212 quad_perm:[1,0,3,2] row_mask:0xf bank_mask:0xf bound_ctrl:1
	v_mul_f32_e32 v210, v60, v106
	v_add_f32_dpp v204, v204, v204 quad_perm:[2,3,0,1] row_mask:0xf bank_mask:0xf bound_ctrl:1
	v_add_f32_dpp v212, v212, v212 quad_perm:[2,3,0,1] row_mask:0xf bank_mask:0xf bound_ctrl:1
	v_mul_f32_e32 v211, v61, v107
	v_add_f32_dpp v204, v204, v204 row_half_mirror row_mask:0xf bank_mask:0xf bound_ctrl:1
	v_add_f32_dpp v212, v212, v212 row_half_mirror row_mask:0xf bank_mask:0xf bound_ctrl:1
	v_fmac_f32_e32 v208, v108, v182
	v_add_f32_dpp v204, v204, v204 row_mirror row_mask:0xf bank_mask:0xf bound_ctrl:1
	v_add_f32_dpp v212, v212, v212 row_mirror row_mask:0xf bank_mask:0xf bound_ctrl:1
	v_fmac_f32_e32 v209, v109, v182
	v_fmac_f32_e32 v210, v110, v182
	v_fmac_f32_e32 v211, v111, v182
	v_cndmask_b32_e64 v215, v215, v212, s[66:67]
	v_fma_f32 v58, v196, v204, v208
	v_fma_f32 v59, v197, v204, v209
	v_fma_f32 v60, v198, v204, v210
	v_fma_f32 v61, v199, v204, v211
	s_waitcnt lgkmcnt(6)
; #define LAS __attribute__((address_space(3)))
; template <int CTRL> __device__ __forceinline__ float dppf(float v) { return __int_as_float(__builtin_amdgcn_update_dpp(0, __float_as_int(v), CTRL, 0xf, 0xf, true)); }
; __device__ __forceinline__ void scan_phase(const Args& a, LAS unsigned char* lds, const bf16* Z, const float* W, const bf16* Aa, const bf16* KK, float* Y, int tid, int lane, int wave) {
;     ...
;                 for (int q = 0; q < SCH; ++q) {
;                     const f32x4 wv = pw[q % 3], kv = pk[q % 3], av = pa[q % 3], bv = pb[q % 3], rv = pr[q % 3]; const float vv = pv[q % 3];
;                     if (q + 2 < SCH) {
;                         const LAS float* p = sb + (q + 2) * SROW; const int i = (q + 2) % 3;
;                         pw[i] = *(const LAS f32x4*)p; pk[i] = *(const LAS f32x4*)(p + 64); pa[i] = *(const LAS f32x4*)(p + 128); pb[i] = *(const LAS f32x4*)(p + 192); pr[i] = *(const LAS f32x4*)(p + 256);
;                         pv[i] = vb[(q + 2) * SROW];
;                     }
;                     f32x2 t2 = S01 * (f32x2){av.x, av.y}; t2 = S23 * (f32x2){av.z, av.w} + t2;
;                     float sa = t2.x + t2.y;
;                     sa += dppf<0xB1>(sa); yd += dppf<0xB1>(yd);
;                     sa += dppf<0x4E>(sa); yd += dppf<0x4E>(yd);
;                     sa += dppf<0x141>(sa); yd += dppf<0x141>(yd);
;                     sa += dppf<0x140>(sa); yd += dppf<0x140>(yd);
;                     if (q > 0) { if (q <= 16) ykA = (j == q - 1) ? yd : ykA; else ykB = (j == q - 17) ? yd : ykB; }
;                     const f32x2 u01 = S01 * (f32x2){wv.x, wv.y} + (f32x2){kv.x, kv.y} * vv, u23 = S23 * (f32x2){wv.z, wv.w} + (f32x2){kv.z, kv.w} * vv;
;                     S01 = u01 + (f32x2){bv.x, bv.y} * sa; S23 = u23 + (f32x2){bv.z, bv.w} * sa;
;                     f32x2 y2 = S01 * (f32x2){rv.x, rv.y}; y2 = S23 * (f32x2){rv.z, rv.w} + y2;
;                     yd = y2.x + y2.y;
;                 }
	v_mul_f32_e32 v212, v58, v200
	v_mul_f32_e32 v213, v59, v201
	v_mul_f32_e32 v204, v58, v72
	v_mul_f32_e32 v205, v59, v73
	v_fmac_f32_e32 v212, v60, v202
	v_fmac_f32_e32 v213, v61, v203
	v_fmac_f32_e32 v204, v60, v74
	v_fmac_f32_e32 v205, v61, v75
	v_add_f32_e32 v212, v212, v213
	v_add_f32_e32 v204, v204, v205
	ds_read_b128 v[104:107], v195 offset:38976
	ds_read_b128 v[108:111], v195 offset:39232
	ds_read_b128 v[112:115], v195 offset:39488
	ds_read_b128 v[196:199], v195 offset:39744
	ds_read_b128 v[200:203], v195 offset:40000
	ds_read_b32 v182, v127 offset:40256
	v_mul_f32_e32 v208, v58, v64
	v_mul_f32_e32 v209, v59, v65
	v_add_f32_dpp v204, v204, v204 quad_perm:[1,0,3,2] row_mask:0xf bank_mask:0xf bound_ctrl:1
	v_add_f32_dpp v212, v212, v212 quad_perm:[1,0,3,2] row_mask:0xf bank_mask:0xf bound_ctrl:1
	v_mul_f32_e32 v210, v60, v66
	v_add_f32_dpp v204, v204, v204 quad_perm:[2,3,0,1] row_mask:0xf bank_mask:0xf bound_ctrl:1
	v_add_f32_dpp v212, v212, v212 quad_perm:[2,3,0,1] row_mask:0xf bank_mask:0xf bound_ctrl:1
	v_mul_f32_e32 v211, v61, v67
	v_add_f32_dpp v204, v204, v204 row_half_mirror row_mask:0xf bank_mask:0xf bound_ctrl:1
	v_add_f32_dpp v212, v212, v212 row_half_mirror row_mask:0xf bank_mask:0xf bound_ctrl:1
	v_fmac_f32_e32 v208, v68, v62
	v_add_f32_dpp v204, v204, v204 row_mirror row_mask:0xf bank_mask:0xf bound_ctrl:1
	v_add_f32_dpp v212, v212, v212 row_mirror row_mask:0xf bank_mask:0xf bound_ctrl:1
	v_fmac_f32_e32 v209, v69, v62
	v_fmac_f32_e32 v210, v70, v62
	v_fmac_f32_e32 v211, v71, v62
	v_cndmask_b32_e64 v215, v215, v212, s[68:69]
	v_fma_f32 v58, v76, v204, v208
	v_fma_f32 v59, v77, v204, v209
	v_fma_f32 v60, v78, v204, v210
	v_fma_f32 v61, v79, v204, v211
	s_waitcnt lgkmcnt(6)
	v_mul_f32_e32 v212, v58, v80
	v_mul_f32_e32 v213, v59, v81
	v_mul_f32_e32 v204, v58, v92
	v_mul_f32_e32 v205, v59, v93
	v_fmac_f32_e32 v212, v60, v82
	v_fmac_f32_e32 v213, v61, v83
	v_fmac_f32_e32 v204, v60, v94
	v_fmac_f32_e32 v205, v61, v95
	v_add_f32_e32 v212, v212, v213
	v_add_f32_e32 v204, v204, v205
	ds_read_b128 v[64:67], v195 offset:40320
	ds_read_b128 v[68:71], v195 offset:40576
	ds_read_b128 v[72:75], v195 offset:40832
	ds_read_b128 v[76:79], v195 offset:41088
	ds_read_b128 v[80:83], v195 offset:41344
	ds_read_b32 v62, v127 offset:41600
	v_mul_f32_e32 v208, v58, v84
	v_mul_f32_e32 v209, v59, v85
	v_add_f32_dpp v204, v204, v204 quad_perm:[1,0,3,2] row_mask:0xf bank_mask:0xf bound_ctrl:1
	v_add_f32_dpp v212, v212, v212 quad_perm:[1,0,3,2] row_mask:0xf bank_mask:0xf bound_ctrl:1
	v_mul_f32_e32 v210, v60, v86
	v_add_f32_dpp v204, v204, v204 quad_perm:[2,3,0,1] row_mask:0xf bank_mask:0xf bound_ctrl:1
	v_add_f32_dpp v212, v212, v212 quad_perm:[2,3,0,1] row_mask:0xf bank_mask:0xf bound_ctrl:1
	v_mul_f32_e32 v211, v61, v87
	v_add_f32_dpp v204, v204, v204 row_half_mirror row_mask:0xf bank_mask:0xf bound_ctrl:1
	v_add_f32_dpp v212, v212, v212 row_half_mirror row_mask:0xf bank_mask:0xf bound_ctrl:1
	v_fmac_f32_e32 v208, v88, v63
	v_add_f32_dpp v204, v204, v204 row_mirror row_mask:0xf bank_mask:0xf bound_ctrl:1
	v_add_f32_dpp v212, v212, v212 row_mirror row_mask:0xf bank_mask:0xf bound_ctrl:1
	v_fmac_f32_e32 v209, v89, v63
	v_fmac_f32_e32 v210, v90, v63
	v_fmac_f32_e32 v211, v91, v63
	v_cndmask_b32_e64 v215, v215, v212, s[70:71]
	v_fma_f32 v58, v96, v204, v208
	v_fma_f32 v59, v97, v204, v209
	v_fma_f32 v60, v98, v204, v210
	v_fma_f32 v61, v99, v204, v211
	s_waitcnt lgkmcnt(6)
	v_mul_f32_e32 v212, v58, v100
	v_mul_f32_e32 v213, v59, v101
	v_mul_f32_e32 v204, v58, v112
	v_mul_f32_e32 v205, v59, v113
	v_fmac_f32_e32 v212, v60, v102
	v_fmac_f32_e32 v213, v61, v103
	v_fmac_f32_e32 v204, v60, v114
	v_fmac_f32_e32 v205, v61, v115
	v_add_f32_e32 v212, v212, v213
	v_add_f32_e32 v204, v204, v205
	ds_read_b128 v[84:87], v195 offset:41664
	ds_read_b128 v[88:91], v195 offset:41920
	ds_read_b128 v[92:95], v195 offset:42176
	ds_read_b128 v[96:99], v195 offset:42432
	ds_read_b128 v[100:103], v195 offset:42688
	ds_read_b32 v63, v127 offset:42944
	v_mul_f32_e32 v208, v58, v104
	v_mul_f32_e32 v209, v59, v105
	v_add_f32_dpp v204, v204, v204 quad_perm:[1,0,3,2] row_mask:0xf bank_mask:0xf bound_ctrl:1
	v_add_f32_dpp v212, v212, v212 quad_perm:[1,0,3,2] row_mask:0xf bank_mask:0xf bound_ctrl:1
	v_mul_f32_e32 v210, v60, v106
	v_add_f32_dpp v204, v204, v204 quad_perm:[2,3,0,1] row_mask:0xf bank_mask:0xf bound_ctrl:1
	v_add_f32_dpp v212, v212, v212 quad_perm:[2,3,0,1] row_mask:0xf bank_mask:0xf bound_ctrl:1
	v_mul_f32_e32 v211, v61, v107
	v_add_f32_dpp v204, v204, v204 row_half_mirror row_mask:0xf bank_mask:0xf bound_ctrl:1
	v_add_f32_dpp v212, v212, v212 row_half_mirror row_mask:0xf bank_mask:0xf bound_ctrl:1
	v_fmac_f32_e32 v208, v108, v182
	v_add_f32_dpp v204, v204, v204 row_mirror row_mask:0xf bank_mask:0xf bound_ctrl:1
	v_add_f32_dpp v212, v212, v212 row_mirror row_mask:0xf bank_mask:0xf bound_ctrl:1
	v_fmac_f32_e32 v209, v109, v182
	v_fmac_f32_e32 v210, v110, v182
	v_fmac_f32_e32 v211, v111, v182
	v_cndmask_b32_e64 v215, v215, v212, s[72:73]
	v_fma_f32 v58, v196, v204, v208
	v_fma_f32 v59, v197, v204, v209
	v_fma_f32 v60, v198, v204, v210
	v_fma_f32 v61, v199, v204, v211
	s_waitcnt lgkmcnt(6)
; #define LAS __attribute__((address_space(3)))
; template <int CTRL> __device__ __forceinline__ float dppf(float v) { return __int_as_float(__builtin_amdgcn_update_dpp(0, __float_as_int(v), CTRL, 0xf, 0xf, true)); }
; __device__ __forceinline__ float red16(float v) { v = red8(v); v += dppf<0x140>(v); return v; }
; __device__ __forceinline__ void scan_phase(const Args& a, LAS unsigned char* lds, const bf16* Z, const float* W, const bf16* Aa, const bf16* KK, float* Y, int tid, int lane, int wave) {
;     ...
;                 for (int q = 0; q < SCH; ++q) {
;                     const f32x4 wv = pw[q % 3], kv = pk[q % 3], av = pa[q % 3], bv = pb[q % 3], rv = pr[q % 3]; const float vv = pv[q % 3];
;                     if (q + 2 < SCH) {
;                         const LAS float* p = sb + (q + 2) * SROW; const int i = (q + 2) % 3;
;                         pw[i] = *(const LAS f32x4*)p; pk[i] = *(const LAS f32x4*)(p + 64); pa[i] = *(const LAS f32x4*)(p + 128); pb[i] = *(const LAS f32x4*)(p + 192); pr[i] = *(const LAS f32x4*)(p + 256);
;                         pv[i] = vb[(q + 2) * SROW];
;                     }
;                     f32x2 t2 = S01 * (f32x2){av.x, av.y}; t2 = S23 * (f32x2){av.z, av.w} + t2;
;                     float sa = t2.x + t2.y;
;                     sa += dppf<0xB1>(sa); yd += dppf<0xB1>(yd);
;                     sa += dppf<0x4E>(sa); yd += dppf<0x4E>(yd);
;                     sa += dppf<0x141>(sa); yd += dppf<0x141>(yd);
;                     sa += dppf<0x140>(sa); yd += dppf<0x140>(yd);
;                     if (q > 0) { if (q <= 16) ykA = (j == q - 1) ? yd : ykA; else ykB = (j == q - 17) ? yd : ykB; }
;                     const f32x2 u01 = S01 * (f32x2){wv.x, wv.y} + (f32x2){kv.x, kv.y} * vv, u23 = S23 * (f32x2){wv.z, wv.w} + (f32x2){kv.z, kv.w} * vv;
;                     S01 = u01 + (f32x2){bv.x, bv.y} * sa; S23 = u23 + (f32x2){bv.z, bv.w} * sa;
;                     f32x2 y2 = S01 * (f32x2){rv.x, rv.y}; y2 = S23 * (f32x2){rv.z, rv.w} + y2;
;                     yd = y2.x + y2.y;
;                 }
;                 yd = red16(yd); ykB = (j == 15) ? yd : ykB;
;                 yp[(size_t)(ch * SCH + j) * 512] = ykA;
;                 yp[(size_t)(ch * SCH + 16 + j) * 512] = ykB;
	v_mul_f32_e32 v212, v58, v200
	v_mul_f32_e32 v213, v59, v201
	v_mul_f32_e32 v204, v58, v72
	v_mul_f32_e32 v205, v59, v73
	v_fmac_f32_e32 v212, v60, v202
	v_fmac_f32_e32 v213, v61, v203
	v_fmac_f32_e32 v204, v60, v74
	v_fmac_f32_e32 v205, v61, v75
	v_add_f32_e32 v212, v212, v213
	v_add_f32_e32 v204, v204, v205
	v_mul_f32_e32 v208, v58, v64
	v_mul_f32_e32 v209, v59, v65
	v_add_f32_dpp v204, v204, v204 quad_perm:[1,0,3,2] row_mask:0xf bank_mask:0xf bound_ctrl:1
	v_add_f32_dpp v212, v212, v212 quad_perm:[1,0,3,2] row_mask:0xf bank_mask:0xf bound_ctrl:1
	v_mul_f32_e32 v210, v60, v66
	v_add_f32_dpp v204, v204, v204 quad_perm:[2,3,0,1] row_mask:0xf bank_mask:0xf bound_ctrl:1
	v_add_f32_dpp v212, v212, v212 quad_perm:[2,3,0,1] row_mask:0xf bank_mask:0xf bound_ctrl:1
	v_mul_f32_e32 v211, v61, v67
	v_add_f32_dpp v204, v204, v204 row_half_mirror row_mask:0xf bank_mask:0xf bound_ctrl:1
	v_add_f32_dpp v212, v212, v212 row_half_mirror row_mask:0xf bank_mask:0xf bound_ctrl:1
	v_fmac_f32_e32 v208, v68, v62
	v_add_f32_dpp v204, v204, v204 row_mirror row_mask:0xf bank_mask:0xf bound_ctrl:1
	v_add_f32_dpp v212, v212, v212 row_mirror row_mask:0xf bank_mask:0xf bound_ctrl:1
	v_fmac_f32_e32 v209, v69, v62
	v_fmac_f32_e32 v210, v70, v62
	v_fmac_f32_e32 v211, v71, v62
	v_cndmask_b32_e64 v215, v215, v212, s[74:75]
	v_fma_f32 v58, v76, v204, v208
	v_fma_f32 v59, v77, v204, v209
	v_fma_f32 v60, v78, v204, v210
	v_fma_f32 v61, v79, v204, v211
	s_waitcnt lgkmcnt(0)
	v_mul_f32_e32 v212, v58, v80
	v_mul_f32_e32 v213, v59, v81
	v_mul_f32_e32 v204, v58, v92
	v_mul_f32_e32 v205, v59, v93
	v_fmac_f32_e32 v212, v60, v82
	v_fmac_f32_e32 v213, v61, v83
	v_fmac_f32_e32 v204, v60, v94
	v_fmac_f32_e32 v205, v61, v95
	v_add_f32_e32 v212, v212, v213
	v_add_f32_e32 v204, v204, v205
	v_mul_f32_e32 v208, v58, v84
	v_mul_f32_e32 v209, v59, v85
	v_add_f32_dpp v204, v204, v204 quad_perm:[1,0,3,2] row_mask:0xf bank_mask:0xf bound_ctrl:1
	v_add_f32_dpp v212, v212, v212 quad_perm:[1,0,3,2] row_mask:0xf bank_mask:0xf bound_ctrl:1
	v_mul_f32_e32 v210, v60, v86
	v_add_f32_dpp v204, v204, v204 quad_perm:[2,3,0,1] row_mask:0xf bank_mask:0xf bound_ctrl:1
	v_add_f32_dpp v212, v212, v212 quad_perm:[2,3,0,1] row_mask:0xf bank_mask:0xf bound_ctrl:1
	v_mul_f32_e32 v211, v61, v87
	v_add_f32_dpp v204, v204, v204 row_half_mirror row_mask:0xf bank_mask:0xf bound_ctrl:1
	v_add_f32_dpp v212, v212, v212 row_half_mirror row_mask:0xf bank_mask:0xf bound_ctrl:1
	v_fmac_f32_e32 v208, v88, v63
	v_add_f32_dpp v204, v204, v204 row_mirror row_mask:0xf bank_mask:0xf bound_ctrl:1
	v_add_f32_dpp v212, v212, v212 row_mirror row_mask:0xf bank_mask:0xf bound_ctrl:1
	v_fmac_f32_e32 v209, v89, v63
	v_fmac_f32_e32 v210, v90, v63
	v_fmac_f32_e32 v211, v91, v63
	v_cndmask_b32_e64 v215, v215, v212, s[76:77]
	v_fma_f32 v58, v96, v204, v208
	v_fma_f32 v59, v97, v204, v209
	v_fma_f32 v60, v98, v204, v210
	v_fma_f32 v61, v99, v204, v211
	v_mul_f32_e32 v212, v58, v100
	v_mul_f32_e32 v213, v59, v101
	v_fmac_f32_e32 v212, v60, v102
	v_fmac_f32_e32 v213, v61, v103
	v_add_f32_e32 v212, v212, v213
	v_lshl_add_u64 v[218:219], v[180:181], 0, s[4:5]
	s_nop 0
	v_add_f32_dpp v212, v212, v212 quad_perm:[1,0,3,2] row_mask:0xf bank_mask:0xf bound_ctrl:1
	v_add_co_u32_e32 v220, vcc, 0x5800000, v218
	s_nop 1
	v_add_f32_dpp v212, v212, v212 quad_perm:[2,3,0,1] row_mask:0xf bank_mask:0xf bound_ctrl:1
	v_addc_co_u32_e32 v221, vcc, 0, v219, vcc
	s_nop 0
	v_add_f32_dpp v212, v212, v212 row_half_mirror row_mask:0xf bank_mask:0xf bound_ctrl:1
	v_add_co_u32_e32 v218, vcc, 0x5808000, v218
	s_nop 1
	v_add_f32_dpp v212, v212, v212 row_mirror row_mask:0xf bank_mask:0xf bound_ctrl:1
	v_addc_co_u32_e32 v219, vcc, 0, v219, vcc
	v_cndmask_b32_e64 v215, v215, v212, s[96:97]
	global_store_dword v[220:221], v214, off
	global_store_dword v[218:219], v215, off
	s_branch .LBB0_224
